# P5 gMLP u operands: 4 x 16-byte loads + v_permlane32_swap between lane halves instead of 8 x 8-byte loads per head (half the cache-line requests)
# speedup vs baseline: 1.0015x; 1.0015x over previous
; __device__ __forceinline__ float bf_lo(unsigned w) { return __uint_as_float(w << 16); }
; __device__ __forceinline__ float bf_hi(unsigned w) { return __uint_as_float(w & 0xffff0000u); }
; template <bool PASS2>
; __device__ __forceinline__ void s5_tile(const Ctx& C, int T, int sb_lo, int sb_hi, LAS unsigned char* lds, int wave, int lane) {
;     ...
; #pragma unroll
;     for (int gi = 0; gi < 4; ++gi) {
;         const int g = wave * 4 + gi;
;         if (!PASS2) { v2f* Ep = (v2f*)C.E() + ((size_t)T * NG + g) * NP + lane; *Ep = (v2f){sr[gi], si[gi]}; }
; __device__ __forceinline__ void gmlp_tile(const Ctx& C, int T, LAS unsigned char* lds, int wave, int lane, int tid) {
;     ...
;     const bf16* zt = C.Z() + (size_t)(r0 + t) * DIN;
;     const int row = tid >> 2, q = tid & 3;
;     const bf16* vsrc = C.Z() + (size_t)(r0 + row) * DIN + 512 + q * 32;
;     const bf16* Weff = C.Weff();
;     v4u vraw[4];
; #pragma unroll
;     for (int i = 0; i < 4; ++i) vraw[i] = *(const v4u*)(vsrc + 8 * i);
; #pragma unroll
;     for (int h = 0; h < 4; ++h) {
;         bfx8 wf[8];
;         const bf16* wrow = Weff + ((size_t)(mode * 4 + h) * 128 + t) * 128 + 8 * hh;
; #pragma unroll
;         for (int ks = 0; ks < 8; ++ks) wf[ks] = *(const bfx8*)(wrow + 16 * ks);
;         v2u uw[2][4];
; #pragma unroll
;         for (int dbi = 0; dbi < 2; ++dbi)
; #pragma unroll
;             for (int rg = 0; rg < 4; ++rg) uw[dbi][rg] = *(const v2u*)(zt + h * 128 + 32 * (2 * dh + dbi) + 8 * rg + 4 * hh);
;         const float bias = C.in(13)[h * 128 + (mode ? (t & 15) : t)];
;         v4f gvv[8];
;         { const float* gvp = C.in(11) + h * 128 + q * 32;
; #pragma unroll
;           for (int i = 0; i < 8; ++i) gvv[i] = *(const v4f*)(gvp + 4 * i); }
;         __syncthreads();
;         {
;             float v[32]; float s = 0.f;
; #pragma unroll
;             for (int i = 0; i < 4; ++i) { const v4u w = vraw[i];
;                 v[8 * i + 0] = bf_lo(w.x); v[8 * i + 1] = bf_hi(w.x); v[8 * i + 2] = bf_lo(w.y); v[8 * i + 3] = bf_hi(w.y);
;                 v[8 * i + 4] = bf_lo(w.z); v[8 * i + 5] = bf_hi(w.z); v[8 * i + 6] = bf_lo(w.w); v[8 * i + 7] = bf_hi(w.w); }
;             if (h < 3) {
; #pragma unroll
;                 for (int i = 0; i < 4; ++i) vraw[i] = *(const v4u*)(vsrc + (h + 1) * 128 + 8 * i);
;             }
; #pragma unroll
;             for (int i = 0; i < 32; ++i) s += v[i] * v[i];
.LBB0_599:
	s_mov_b64 s[0:1], s[80:81]
	s_load_dwordx2 s[0:1], s[0:1], 0x110
	s_lshl_b32 s28, s42, 2
	s_ashr_i32 s25, s24, 31
	s_lshl_b64 s[52:53], s[24:25], 14
	s_ashr_i32 s29, s28, 31
	s_waitcnt lgkmcnt(0)
	s_add_u32 s3, s0, s52
	s_addc_u32 s25, s1, s53
	s_lshl_b64 s[0:1], s[28:29], 9
	s_add_u32 s0, s3, s0
	s_addc_u32 s1, s25, s1
	v_lshlrev_b32_e32 v82, 3, v80
	v_lshl_add_u64 v[0:1], s[0:1], 0, v[82:83]
	v_add_co_u32_e32 v0, vcc, s35, v0
	v_pk_mov_b32 v[2:3], v[166:167], v[166:167] op_sel:[1,0]
	s_nop 0
	v_addc_co_u32_e32 v1, vcc, 0, v1, vcc
	s_mov_b64 s[0:1], s[80:81]
	global_store_dwordx2 v[0:1], v[2:3], off
	s_load_dwordx2 s[0:1], s[0:1], 0x110
	s_or_b32 s54, s28, 1
	s_ashr_i32 s55, s54, 31
	v_pk_mov_b32 v[2:3], v[164:165], v[164:165] op_sel:[1,0]
	v_mov_b32_e32 v97, v83
	s_waitcnt lgkmcnt(0)
	s_add_u32 s3, s0, s52
	s_addc_u32 s25, s1, s53
	s_lshl_b64 s[0:1], s[54:55], 9
	s_add_u32 s0, s3, s0
	s_addc_u32 s1, s25, s1
	v_lshl_add_u64 v[0:1], s[0:1], 0, v[82:83]
	v_add_co_u32_e32 v0, vcc, s35, v0
	s_mov_b64 s[0:1], s[80:81]
	s_nop 0
	v_addc_co_u32_e32 v1, vcc, 0, v1, vcc
	global_store_dwordx2 v[0:1], v[2:3], off
	s_load_dwordx2 s[0:1], s[0:1], 0x110
	s_or_b32 s54, s28, 2
	s_ashr_i32 s55, s54, 31
	v_pk_mov_b32 v[2:3], v[162:163], v[162:163] op_sel:[1,0]
	v_mov_b32_e32 v101, v83
	s_waitcnt lgkmcnt(0)
	s_add_u32 s3, s0, s52
	s_addc_u32 s25, s1, s53
	s_lshl_b64 s[0:1], s[54:55], 9
	s_add_u32 s0, s3, s0
	s_addc_u32 s1, s25, s1
	v_lshl_add_u64 v[0:1], s[0:1], 0, v[82:83]
	v_add_co_u32_e32 v0, vcc, s35, v0
	s_mov_b64 s[0:1], s[80:81]
	s_nop 0
	v_addc_co_u32_e32 v1, vcc, 0, v1, vcc
	global_store_dwordx2 v[0:1], v[2:3], off
	s_load_dwordx2 s[0:1], s[0:1], 0x110
	s_or_b32 s28, s28, 3
	s_ashr_i32 s29, s28, 31
	v_pk_mov_b32 v[2:3], v[160:161], v[160:161] op_sel:[1,0]
	v_lshlrev_b32_e32 v139, 2, v86
	s_waitcnt lgkmcnt(0)
	s_add_u32 s3, s0, s52
	s_addc_u32 s25, s1, s53
	s_lshl_b64 s[0:1], s[28:29], 9
	s_add_u32 s0, s3, s0
	s_addc_u32 s1, s25, s1
	v_lshl_add_u64 v[0:1], s[0:1], 0, v[82:83]
	v_add_co_u32_e32 v0, vcc, s35, v0
	s_mov_b64 s[0:1], s[80:81]
	s_nop 0
	v_addc_co_u32_e32 v1, vcc, 0, v1, vcc
	global_store_dwordx2 v[0:1], v[2:3], off
	s_barrier
	s_mov_b64 s[28:29], s[80:81]
	s_load_dwordx2 s[0:1], s[0:1], 0x110
	s_load_dwordx2 s[28:29], s[28:29], 0x110
	v_add_u32_e32 v2, s26, v173
	v_lshlrev_b32_e32 v82, 1, v86
	s_lshl_b32 s3, s42, 5
	s_and_b32 s3, s3, 0x60
	s_waitcnt lgkmcnt(0)
	v_mov_b64_e32 v[0:1], s[28:29]
	v_mad_i64_i32 v[0:1], s[28:29], v2, s34, v[0:1]
	v_lshl_add_u64 v[0:1], v[0:1], 0, v[82:83]
	v_add_co_u32_e32 v2, vcc, s36, v0
	s_mov_b64 s[28:29], s[80:81]
	s_nop 0
	v_addc_co_u32_e32 v3, vcc, 0, v1, vcc
	global_load_dwordx4 v[8:11], v[2:3], off offset:1024
	v_lshl_add_u64 v[108:109], v[0:1], 0, s[18:19]
	global_load_dwordx4 v[12:15], v[108:109], off offset:16
	global_load_dwordx4 v[16:19], v[108:109], off offset:32
	global_load_dwordx4 v[20:23], v[108:109], off offset:48
	v_or_b32_e32 v132, s3, v85
	v_or_b32_e32 v2, s26, v132
	s_load_dwordx2 s[26:27], s[28:29], 0x110
	v_mov_b64_e32 v[0:1], s[0:1]
	s_ashr_i32 s13, s13, 8
	v_mad_i64_i32 v[0:1], s[0:1], v2, s34, v[0:1]
	s_waitcnt lgkmcnt(0)
	v_lshl_add_u64 v[2:3], s[26:27], 0, v[96:97]
	v_lshlrev_b32_e32 v82, 8, v132
	s_lshl_b32 s26, s13, 6
	v_lshl_add_u64 v[104:105], v[2:3], 0, v[82:83]
	v_bfe_u32 v234, v81, 5, 1
	v_mul_u32_u24_e32 v234, 0x1f0, v234
	v_mul_u32_u24_e32 v235, 0xf0, v85
	v_sub_u32_e32 v234, v234, v235
	v_add_u32_e32 v234, 0xe00, v234
	v_ashrrev_i32_e32 v235, 31, v234
	v_lshl_add_u64 v[104:105], v[234:235], 0, v[104:105]
	v_lshl_add_u64 v[4:5], v[0:1], 0, v[100:101]
	v_add_co_u32_e32 v0, vcc, s37, v104
	s_ashr_i32 s27, s26, 31
	v_lshl_add_u64 v[6:7], v[104:105], 0, s[20:21]
	v_addc_co_u32_e32 v1, vcc, 0, v105, vcc
	v_lshl_add_u64 v[4:5], s[26:27], 1, v[4:5]
	global_load_dwordx4 v[64:67], v[6:7], off offset:-2560
	global_load_dwordx4 v[60:63], v[6:7], off offset:-1536
	global_load_dwordx4 v[56:59], v[6:7], off offset:-512
	global_load_dwordx4 v[48:51], v[6:7], off offset:512
	global_load_dwordx4 v[44:47], v[6:7], off offset:1536
	global_load_dwordx4 v[36:39], v[6:7], off offset:2560
	s_nop 0
	global_load_dwordx4 v[0:3], v[0:1], off offset:-3584
	s_nop 0
	global_load_dwordx4 v[28:31], v[6:7], off offset:3584
	v_add_co_u32_e32 v6, vcc, s36, v4
	v_lshl_add_u64 v[106:107], v[4:5], 0, s[22:23]
	v_bfe_u32 v236, v81, 5, 1
	v_lshlrev_b32_e32 v236, 3, v236
	v_mov_b32_e32 v237, 0
	v_lshl_add_u64 v[236:237], v[106:107], 0, v[236:237]
	s_nop 0
	v_addc_co_u32_e32 v7, vcc, 0, v5, vcc
	s_mov_b64 s[0:1], s[80:81]
	global_load_dwordx4 v[238:241], v[236:237], off offset:0
	global_load_dwordx4 v[242:245], v[236:237], off offset:32
	global_load_dwordx4 v[246:249], v[236:237], off offset:64
	global_load_dwordx4 v[250:253], v[236:237], off offset:96
	s_nop 0
	s_nop 0
	s_load_dwordx2 s[0:1], s[0:1], 0x68
	v_lshlrev_b32_e32 v156, 2, v132
	v_or_b32_e32 v157, s26, v85
	s_waitcnt lgkmcnt(0)
	global_load_dword v128, v156, s[0:1]
	s_mov_b64 s[0:1], s[80:81]
	s_load_dwordx2 s[28:29], s[0:1], 0x58
	s_waitcnt lgkmcnt(0)
	global_load_dwordx4 v[114:117], v139, s[28:29] offset:48
	global_load_dwordx4 v[118:121], v139, s[28:29] offset:32
	global_load_dwordx4 v[122:125], v139, s[28:29] offset:16
	global_load_dwordx4 v[134:137], v139, s[28:29]
	s_waitcnt vmcnt(20)
	v_and_b32_e32 v97, 0xffff0000, v8
	v_lshlrev_b32_e32 v82, 16, v8
	v_lshlrev_b32_e32 v130, 16, v10
	v_and_b32_e32 v131, 0xffff0000, v10
	v_mul_f32_e32 v10, v97, v97
	v_lshlrev_b32_e32 v101, 16, v9
	v_fmac_f32_e32 v10, v82, v82
	v_and_b32_e32 v129, 0xffff0000, v9
	v_fmac_f32_e32 v10, v101, v101
	v_fmac_f32_e32 v10, v129, v129
	v_fmac_f32_e32 v10, v130, v130
	v_lshlrev_b32_e32 v133, 16, v11
	v_fmac_f32_e32 v10, v131, v131
	v_and_b32_e32 v138, 0xffff0000, v11
	v_fmac_f32_e32 v10, v133, v133
	s_waitcnt vmcnt(19)
; __device__ __forceinline__ float bf_lo(unsigned w) { return __uint_as_float(w << 16); }
; __device__ __forceinline__ float bf_hi(unsigned w) { return __uint_as_float(w & 0xffff0000u); }
; __device__ __forceinline__ bf16 f2bf(float f) { return (bf16)(cvt_pk_nv(f, 0.f) & 0xffffu); }
; __device__ __forceinline__ void gmlp_tile(const Ctx& C, int T, LAS unsigned char* lds, int wave, int lane, int tid) {
;     ...
;         __syncthreads();
;         {
;             float v[32]; float s = 0.f;
; #pragma unroll
;             for (int i = 0; i < 4; ++i) { const v4u w = vraw[i];
;                 v[8 * i + 0] = bf_lo(w.x); v[8 * i + 1] = bf_hi(w.x); v[8 * i + 2] = bf_lo(w.y); v[8 * i + 3] = bf_hi(w.y);
;                 v[8 * i + 4] = bf_lo(w.z); v[8 * i + 5] = bf_hi(w.z); v[8 * i + 6] = bf_lo(w.w); v[8 * i + 7] = bf_hi(w.w); }
;             if (h < 3) {
; #pragma unroll
;                 for (int i = 0; i < 4; ++i) vraw[i] = *(const v4u*)(vsrc + (h + 1) * 128 + 8 * i);
;             }
; #pragma unroll
;             for (int i = 0; i < 32; ++i) s += v[i] * v[i];
;             s += __shfl_xor(s, 1); s += __shfl_xor(s, 2);
;             const float r = rsqrtf(s * (1.f / 128.f) + EPS);
; #pragma unroll
;             for (int i = 0; i < 32; ++i) { v[i] = v[i] * r * gvv[i >> 2][i & 3]; VT[(q * 32 + i) * VT_STRIDE + row] = f2bf(v[i]); }
	v_lshlrev_b32_e32 v140, 16, v12
	v_fmac_f32_e32 v10, v138, v138
	v_and_b32_e32 v141, 0xffff0000, v12
	v_fmac_f32_e32 v10, v140, v140
	v_lshlrev_b32_e32 v142, 16, v13
	v_fmac_f32_e32 v10, v141, v141
	v_and_b32_e32 v143, 0xffff0000, v13
	v_fmac_f32_e32 v10, v142, v142
	v_lshlrev_b32_e32 v144, 16, v14
	v_fmac_f32_e32 v10, v143, v143
	v_and_b32_e32 v145, 0xffff0000, v14
	v_fmac_f32_e32 v10, v144, v144
	v_lshlrev_b32_e32 v146, 16, v15
	v_fmac_f32_e32 v10, v145, v145
	v_and_b32_e32 v147, 0xffff0000, v15
	v_fmac_f32_e32 v10, v146, v146
	s_waitcnt vmcnt(18)
	v_lshlrev_b32_e32 v148, 16, v16
	v_fmac_f32_e32 v10, v147, v147
	v_and_b32_e32 v149, 0xffff0000, v16
	v_fmac_f32_e32 v10, v148, v148
	v_lshlrev_b32_e32 v150, 16, v17
	v_fmac_f32_e32 v10, v149, v149
	v_and_b32_e32 v151, 0xffff0000, v17
	v_fmac_f32_e32 v10, v150, v150
	v_lshlrev_b32_e32 v152, 16, v18
	v_fmac_f32_e32 v10, v151, v151
	v_and_b32_e32 v153, 0xffff0000, v18
	v_fmac_f32_e32 v10, v152, v152
	v_lshlrev_b32_e32 v154, 16, v19
	v_fmac_f32_e32 v10, v153, v153
	v_and_b32_e32 v155, 0xffff0000, v19
	v_fmac_f32_e32 v10, v154, v154
	s_waitcnt vmcnt(17)
	v_and_b32_e32 v74, 0xffff0000, v20
	v_lshlrev_b32_e32 v75, 16, v20
	v_fmac_f32_e32 v10, v155, v155
	v_pk_mul_f32 v[8:9], v[74:75], v[74:75]
	v_and_b32_e32 v102, 0xffff0000, v21
	v_add_f32_e32 v9, v9, v10
	v_lshlrev_b32_e32 v103, 16, v21
	v_add_f32_e32 v10, v8, v9
	v_pk_mul_f32 v[8:9], v[102:103], v[102:103]
	v_and_b32_e32 v110, 0xffff0000, v22
	v_add_f32_e32 v9, v9, v10
	v_lshlrev_b32_e32 v111, 16, v22
	v_add_f32_e32 v10, v8, v9
	v_pk_mul_f32 v[8:9], v[110:111], v[110:111]
	v_and_b32_e32 v126, 0xffff0000, v23
	v_add_f32_e32 v9, v9, v10
	v_lshlrev_b32_e32 v127, 16, v23
	v_add_f32_e32 v10, v8, v9
	v_pk_mul_f32 v[8:9], v[126:127], v[126:127]
	s_nop 0
	v_add_f32_e32 v9, v9, v10
	v_add_f32_e32 v16, v8, v9
	ds_bpermute_b32 v17, v183, v16
	global_load_dwordx4 v[8:11], v139, s[28:29] offset:112
	global_load_dwordx4 v[12:15], v139, s[28:29] offset:96
	s_waitcnt lgkmcnt(0)
	v_add_f32_e32 v24, v16, v17
	global_load_dwordx4 v[16:19], v139, s[28:29] offset:80
	global_load_dwordx4 v[20:23], v139, s[28:29] offset:64
	ds_bpermute_b32 v25, v184, v24
	s_waitcnt lgkmcnt(0)
	s_barrier
	v_add_f32_e32 v24, v24, v25
	v_fmamk_f32 v24, v24, 0x3c000000, v177
	v_mul_f32_e32 v25, 0x4b800000, v24
	v_cmp_gt_f32_e32 vcc, s38, v24
	s_nop 1
	v_cndmask_b32_e32 v24, v24, v25, vcc
	v_rsq_f32_e32 v158, v24
	global_load_dwordx4 v[24:27], v[108:109], off offset:304
	global_load_dwordx4 v[32:35], v[108:109], off offset:288
	global_load_dwordx4 v[40:43], v[108:109], off offset:272
	global_load_dwordx4 v[52:55], v[108:109], off offset:256
	v_mul_f32_e32 v159, 0x45800000, v158
	v_cndmask_b32_e32 v158, v158, v159, vcc
	v_mul_f32_e32 v82, v158, v82
	s_waitcnt vmcnt(8)
	v_permlane32_swap_b32_e32 v238, v240
	v_permlane32_swap_b32_e32 v239, v241
	v_permlane32_swap_b32_e32 v242, v244
	v_permlane32_swap_b32_e32 v243, v245
	v_permlane32_swap_b32_e32 v246, v248
	v_permlane32_swap_b32_e32 v247, v249
	v_permlane32_swap_b32_e32 v250, v252
	v_permlane32_swap_b32_e32 v251, v253
	v_mov_b32_e32 v6, v238
	v_mov_b32_e32 v7, v239
	v_mov_b32_e32 v4, v240
	v_mov_b32_e32 v5, v241
	v_mov_b32_e32 v72, v242
	v_mov_b32_e32 v73, v243
	v_mov_b32_e32 v70, v244
	v_mov_b32_e32 v71, v245
	v_mov_b32_e32 v68, v246
	v_mov_b32_e32 v69, v247
	v_mov_b32_e32 v112, v248
	v_mov_b32_e32 v113, v249
	v_mov_b32_e32 v78, v250
	v_mov_b32_e32 v79, v251
	v_mov_b32_e32 v76, v252
	v_mov_b32_e32 v77, v253
	v_mul_f32_e32 v82, v134, v82
	v_cvt_pk_bf16_f32 v82, v82, v83
	ds_write_b16 v174, v82
	v_mul_f32_e32 v82, v158, v97
	v_mul_f32_e32 v82, v135, v82
	v_cvt_pk_bf16_f32 v82, v82, v83
	ds_write_b16 v174, v82 offset:272
	v_mul_f32_e32 v82, v158, v101
	v_mul_f32_e32 v82, v136, v82
	v_cvt_pk_bf16_f32 v82, v82, v83
	ds_write_b16 v174, v82 offset:544
	v_mul_f32_e32 v82, v158, v129
	v_mul_f32_e32 v82, v137, v82
	v_cvt_pk_bf16_f32 v82, v82, v83
	ds_write_b16 v174, v82 offset:816
	v_mul_f32_e32 v82, v158, v130
	v_mul_f32_e32 v82, v122, v82
	v_cvt_pk_bf16_f32 v82, v82, v83
	ds_write_b16 v174, v82 offset:1088
	v_mul_f32_e32 v82, v158, v131
	v_mul_f32_e32 v82, v123, v82
	v_cvt_pk_bf16_f32 v82, v82, v83
	ds_write_b16 v174, v82 offset:1360
	v_mul_f32_e32 v82, v158, v133
	v_mul_f32_e32 v82, v124, v82
	v_cvt_pk_bf16_f32 v82, v82, v83
	ds_write_b16 v174, v82 offset:1632
	v_mul_f32_e32 v82, v158, v138
	v_mul_f32_e32 v82, v125, v82
	v_cvt_pk_bf16_f32 v82, v82, v83
	ds_write_b16 v174, v82 offset:1904
	v_mul_f32_e32 v82, v158, v140
	v_mul_f32_e32 v82, v118, v82
	v_cvt_pk_bf16_f32 v82, v82, v83
	ds_write_b16 v174, v82 offset:2176
	v_mul_f32_e32 v82, v158, v141
	v_mul_f32_e32 v82, v119, v82
	v_cvt_pk_bf16_f32 v82, v82, v83
	ds_write_b16 v174, v82 offset:2448
	v_mul_f32_e32 v82, v158, v142
	v_mul_f32_e32 v82, v120, v82
	v_cvt_pk_bf16_f32 v82, v82, v83
	ds_write_b16 v174, v82 offset:2720
	v_mul_f32_e32 v82, v158, v143
	v_mul_f32_e32 v82, v121, v82
	v_cvt_pk_bf16_f32 v82, v82, v83
	ds_write_b16 v174, v82 offset:2992
	v_mul_f32_e32 v82, v158, v144
	v_mul_f32_e32 v82, v114, v82
	v_cvt_pk_bf16_f32 v82, v82, v83
	ds_write_b16 v174, v82 offset:3264
	v_mul_f32_e32 v82, v158, v145
	v_mul_f32_e32 v82, v115, v82
	v_cvt_pk_bf16_f32 v82, v82, v83
	ds_write_b16 v174, v82 offset:3536
	v_mul_f32_e32 v82, v158, v146
	v_mul_f32_e32 v82, v116, v82
	v_cvt_pk_bf16_f32 v82, v82, v83
	ds_write_b16 v174, v82 offset:3808
	v_mul_f32_e32 v82, v158, v147
	v_mul_f32_e32 v82, v117, v82
	v_cvt_pk_bf16_f32 v82, v82, v83
	ds_write_b16 v174, v82 offset:4080
	v_mul_f32_e32 v82, v158, v148
	s_waitcnt vmcnt(4)
; __device__ __forceinline__ float bf_lo(unsigned w) { return __uint_as_float(w << 16); }
; __device__ __forceinline__ float bf_hi(unsigned w) { return __uint_as_float(w & 0xffff0000u); }
; #define LAS __attribute__((address_space(3)))
; __device__ __forceinline__ unsigned cvt_pk_nv(float lo, float hi) { unsigned r; asm("v_cvt_pk_bf16_f32 %0, %1, %2" : "=v"(r) : "v"(lo), "v"(hi)); return r; }
; __device__ __forceinline__ bf16 f2bf(float f) { return (bf16)(cvt_pk_nv(f, 0.f) & 0xffffu); }
;     __device__ __forceinline__ float* out() const { return (float*)karg_in(33); }
; __device__ __forceinline__ void gmlp_tile(const Ctx& C, int T, LAS unsigned char* lds, int wave, int lane, int tid) {
;     ...
;             for (int i = 0; i < 32; ++i) { v[i] = v[i] * r * gvv[i >> 2][i & 3]; VT[(q * 32 + i) * VT_STRIDE + row] = f2bf(v[i]); }
;             if (mode) { float* ov = C.out() + OFF_V_S + (size_t)row * AW + h * 128 + q * 32;
; #pragma unroll
;                 for (int i = 0; i < 8; ++i) *(v4f*)(ov + 4 * i) = (v4f){v[4 * i], v[4 * i + 1], v[4 * i + 2], v[4 * i + 3]}; }
;         }
;         __syncthreads();
; #pragma unroll
;         for (int dbi = 0; dbi < 2; ++dbi) {
;             const int db = 2 * dh + dbi;
;             v16f acc;
; #pragma unroll
;             for (int r = 0; r < 16; ++r) acc[r] = 0.f;
; #pragma unroll
;             for (int ks = 0; ks < 8; ++ks) {
;                 const bfx8 va = *(const LAS bfx8*)(VT + (32 * db + tl) * VT_STRIDE + 16 * ks + 8 * hh);
;                 acc = __builtin_amdgcn_mfma_f32_32x32x16_bf16(va, wf[ks], acc, 0, 0, 0);
;             }
; #pragma unroll
;             for (int rg = 0; rg < 4; ++rg) {
;                 const v2u u2 = uw[dbi][rg];
;                 const float o0 = bf_lo(u2.x) * (acc[4 * rg + 0] + bias), o1 = bf_hi(u2.x) * (acc[4 * rg + 1] + bias);
;                 const float o2 = bf_lo(u2.y) * (acc[4 * rg + 2] + bias), o3 = bf_hi(u2.y) * (acc[4 * rg + 3] + bias);
;                 ssq += (o0 * o0 + o1 * o1) + (o2 * o2 + o3 * o3);
;                 outp[h][dbi][2 * rg] = cvt_pk_nv(o0, o1); outp[h][dbi][2 * rg + 1] = cvt_pk_nv(o2, o3);
;             }
	v_mul_f32_e32 v20, v20, v82
	v_cvt_pk_bf16_f32 v20, v20, v83
	ds_write_b16 v174, v20 offset:4352
	v_mul_f32_e32 v20, v158, v149
	v_mul_f32_e32 v20, v21, v20
	v_cvt_pk_bf16_f32 v20, v20, v83
	ds_write_b16 v174, v20 offset:4624
	v_mul_f32_e32 v20, v158, v150
	v_mul_f32_e32 v20, v22, v20
	v_cvt_pk_bf16_f32 v20, v20, v83
	ds_write_b16 v174, v20 offset:4896
	v_mul_f32_e32 v20, v158, v151
	v_mul_f32_e32 v20, v23, v20
	v_cvt_pk_bf16_f32 v20, v20, v83
	ds_write_b16 v174, v20 offset:5168
	v_mul_f32_e32 v20, v158, v152
	v_mul_f32_e32 v16, v16, v20
	v_cvt_pk_bf16_f32 v16, v16, v83
	ds_write_b16 v174, v16 offset:5440
	v_mul_f32_e32 v16, v158, v153
	v_mul_f32_e32 v16, v17, v16
	v_cvt_pk_bf16_f32 v16, v16, v83
	ds_write_b16 v174, v16 offset:5712
	v_mul_f32_e32 v16, v158, v154
	v_mul_f32_e32 v16, v18, v16
	v_cvt_pk_bf16_f32 v16, v16, v83
	ds_write_b16 v174, v16 offset:5984
	v_mul_f32_e32 v16, v158, v155
	v_mul_f32_e32 v16, v19, v16
	v_cvt_pk_bf16_f32 v16, v16, v83
	ds_write_b16 v174, v16 offset:6256
	v_mul_f32_e32 v16, v158, v75
	v_mul_f32_e32 v12, v12, v16
	v_cvt_pk_bf16_f32 v12, v12, v83
	ds_write_b16 v174, v12 offset:6528
	v_mul_f32_e32 v12, v158, v74
	v_mul_f32_e32 v12, v13, v12
	v_cvt_pk_bf16_f32 v12, v12, v83
	ds_write_b16 v174, v12 offset:6800
	v_mul_f32_e32 v12, v158, v103
	v_mul_f32_e32 v12, v14, v12
	v_cvt_pk_bf16_f32 v12, v12, v83
	ds_write_b16 v174, v12 offset:7072
	v_mul_f32_e32 v12, v158, v102
	v_mul_f32_e32 v12, v15, v12
	v_cvt_pk_bf16_f32 v12, v12, v83
	ds_write_b16 v174, v12 offset:7344
	v_mul_f32_e32 v12, v158, v111
	v_mul_f32_e32 v8, v8, v12
	v_cvt_pk_bf16_f32 v8, v8, v83
	ds_write_b16 v174, v8 offset:7616
	v_mul_f32_e32 v8, v158, v110
	v_mul_f32_e32 v8, v9, v8
	v_cvt_pk_bf16_f32 v8, v8, v83
	ds_write_b16 v174, v8 offset:7888
	v_mul_f32_e32 v8, v158, v127
	v_mul_f32_e32 v8, v10, v8
	v_cvt_pk_bf16_f32 v8, v8, v83
	ds_write_b16 v174, v8 offset:8160
	v_mul_f32_e32 v8, v158, v126
	v_mul_f32_e32 v8, v11, v8
	v_cvt_pk_bf16_f32 v8, v8, v83
	v_mad_u64_u32 v[102:103], s[0:1], v157, s30, v[90:91]
	ds_write_b16 v174, v8 offset:8432
	s_waitcnt lgkmcnt(0)
	s_barrier
	ds_read_b128 v[8:11], v102
	ds_read_b128 v[114:117], v102 offset:32
	s_waitcnt lgkmcnt(1)
	v_mfma_f32_32x32x16_bf16 v[8:23], v[8:11], v[0:3], 0
	v_lshlrev_b32_e32 v74, 16, v6
	v_and_b32_e32 v6, 0xffff0000, v6
	s_mov_b64 s[0:1], s[80:81]
	s_waitcnt vmcnt(0)
	v_and_b32_e32 v164, 0xffff0000, v52
	v_lshlrev_b32_e32 v158, 16, v52
	v_lshlrev_b32_e32 v200, 16, v34
	v_and_b32_e32 v201, 0xffff0000, v34
	s_waitcnt lgkmcnt(0)
	v_mfma_f32_32x32x16_bf16 v[8:23], v[114:117], v[64:67], v[8:23]
	ds_read_b128 v[114:117], v102 offset:64
	ds_read_b128 v[118:121], v102 offset:96
	v_mul_f32_e32 v34, v164, v164
	v_lshlrev_b32_e32 v165, 16, v53
	v_fmac_f32_e32 v34, v158, v158
	v_and_b32_e32 v166, 0xffff0000, v53
	v_fmac_f32_e32 v34, v165, v165
	v_lshlrev_b32_e32 v167, 16, v54
	s_waitcnt lgkmcnt(1)
	v_mfma_f32_32x32x16_bf16 v[8:23], v[114:117], v[60:63], v[8:23]
	v_fmac_f32_e32 v34, v166, v166
	v_and_b32_e32 v178, 0xffff0000, v54
	v_fmac_f32_e32 v34, v167, v167
	v_lshlrev_b32_e32 v179, 16, v55
	v_fmac_f32_e32 v34, v178, v178
	v_and_b32_e32 v180, 0xffff0000, v55
	v_fmac_f32_e32 v34, v179, v179
	s_waitcnt lgkmcnt(0)
	v_mfma_f32_32x32x16_bf16 v[8:23], v[118:121], v[56:59], v[8:23]
	ds_read_b128 v[114:117], v102 offset:128
	ds_read_b128 v[118:121], v102 offset:160
	v_lshlrev_b32_e32 v181, 16, v40
	v_fmac_f32_e32 v34, v180, v180
	v_and_b32_e32 v189, 0xffff0000, v40
	v_fmac_f32_e32 v34, v181, v181
	v_lshlrev_b32_e32 v190, 16, v41
	v_fmac_f32_e32 v34, v189, v189
	s_waitcnt lgkmcnt(1)
	v_mfma_f32_32x32x16_bf16 v[8:23], v[114:117], v[48:51], v[8:23]
	v_and_b32_e32 v191, 0xffff0000, v41
	v_fmac_f32_e32 v34, v190, v190
	v_lshlrev_b32_e32 v192, 16, v42
	v_fmac_f32_e32 v34, v191, v191
	v_and_b32_e32 v193, 0xffff0000, v42
	v_fmac_f32_e32 v34, v192, v192
	v_lshlrev_b32_e32 v194, 16, v43
	s_waitcnt lgkmcnt(0)
	v_mfma_f32_32x32x16_bf16 v[8:23], v[118:121], v[44:47], v[8:23]
	ds_read_b128 v[114:117], v102 offset:192
	ds_read_b128 v[118:121], v102 offset:224
	v_fmac_f32_e32 v34, v193, v193
	v_and_b32_e32 v195, 0xffff0000, v43
	v_fmac_f32_e32 v34, v194, v194
	v_lshlrev_b32_e32 v196, 16, v32
	v_fmac_f32_e32 v34, v195, v195
	v_and_b32_e32 v197, 0xffff0000, v32
	s_waitcnt lgkmcnt(1)
	v_mfma_f32_32x32x16_bf16 v[8:23], v[114:117], v[36:39], v[8:23]
	ds_read_b128 v[114:117], v102 offset:8736
	v_fmac_f32_e32 v34, v196, v196
	v_lshlrev_b32_e32 v198, 16, v33
	v_fmac_f32_e32 v34, v197, v197
	v_and_b32_e32 v199, 0xffff0000, v33
	v_fmac_f32_e32 v34, v198, v198
	v_fmac_f32_e32 v34, v199, v199
	s_waitcnt lgkmcnt(1)
	v_mfma_f32_32x32x16_bf16 v[8:23], v[118:121], v[28:31], v[8:23]
	ds_read_b128 v[118:121], v102 offset:8768
	v_fmac_f32_e32 v34, v200, v200
	v_lshlrev_b32_e32 v202, 16, v35
	v_fmac_f32_e32 v34, v201, v201
	v_and_b32_e32 v203, 0xffff0000, v35
	v_fmac_f32_e32 v34, v202, v202
	v_fmac_f32_e32 v34, v203, v203
	s_nop 4
	v_add_f32_e32 v9, v128, v9
	v_mul_f32_e32 v6, v9, v6
	v_lshlrev_b32_e32 v9, 16, v7
	v_add_f32_e32 v10, v128, v10
	v_mul_f32_e32 v9, v10, v9
	v_and_b32_e32 v7, 0xffff0000, v7
	v_add_f32_e32 v10, v128, v11
	v_add_f32_e32 v8, v128, v8
	v_mul_f32_e32 v7, v10, v7
	v_mul_f32_e32 v8, v8, v74
	v_mul_f32_e32 v10, v6, v6
	v_mul_f32_e32 v11, v7, v7
	v_cvt_pk_bf16_f32 v97, v8, v6
	v_cvt_pk_bf16_f32 v82, v9, v7
	v_lshlrev_b32_e32 v6, 16, v4
	v_add_f32_e32 v7, v128, v12
	v_mul_f32_e32 v75, v7, v6
	v_and_b32_e32 v4, 0xffff0000, v4
	v_add_f32_e32 v6, v128, v13
	v_mul_f32_e32 v101, v6, v4
	v_lshlrev_b32_e32 v4, 16, v5
	v_add_f32_e32 v6, v128, v14
	v_fmac_f32_e32 v10, v8, v8
	v_mul_f32_e32 v103, v6, v4
	v_and_b32_e32 v8, 0xffff0000, v5
	ds_read_b128 v[4:7], v102 offset:8704
	v_fmac_f32_e32 v11, v9, v9
	v_add_f32_e32 v9, v128, v15
	v_mul_f32_e32 v110, v9, v8
	v_mul_f32_e32 v8, v101, v101
	v_mul_f32_e32 v9, v110, v110
	v_fmac_f32_e32 v8, v75, v75
	v_fmac_f32_e32 v9, v103, v103
	v_add_f32_e32 v74, v10, v11
	v_add_f32_e32 v111, v8, v9
	s_waitcnt lgkmcnt(0)
; __device__ __forceinline__ float bf_lo(unsigned w) { return __uint_as_float(w << 16); }
; __device__ __forceinline__ float bf_hi(unsigned w) { return __uint_as_float(w & 0xffff0000u); }
; #define LAS __attribute__((address_space(3)))
; __device__ __forceinline__ unsigned cvt_pk_nv(float lo, float hi) { unsigned r; asm("v_cvt_pk_bf16_f32 %0, %1, %2" : "=v"(r) : "v"(lo), "v"(hi)); return r; }
;     __device__ __forceinline__ const float* in(int i) const { return karg_in(i); }
; __device__ __forceinline__ void gmlp_tile(const Ctx& C, int T, LAS unsigned char* lds, int wave, int lane, int tid) {
;     ...
;         const bf16* wrow = Weff + ((size_t)(mode * 4 + h) * 128 + t) * 128 + 8 * hh;
; #pragma unroll
;         for (int ks = 0; ks < 8; ++ks) wf[ks] = *(const bfx8*)(wrow + 16 * ks);
;         v2u uw[2][4];
; #pragma unroll
;         for (int dbi = 0; dbi < 2; ++dbi)
; #pragma unroll
;             for (int rg = 0; rg < 4; ++rg) uw[dbi][rg] = *(const v2u*)(zt + h * 128 + 32 * (2 * dh + dbi) + 8 * rg + 4 * hh);
;         const float bias = C.in(13)[h * 128 + (mode ? (t & 15) : t)];
;         v4f gvv[8];
;         { const float* gvp = C.in(11) + h * 128 + q * 32;
; #pragma unroll
;           for (int i = 0; i < 8; ++i) gvv[i] = *(const v4f*)(gvp + 4 * i); }
;     ...
;         for (int dbi = 0; dbi < 2; ++dbi) {
;             const int db = 2 * dh + dbi;
;             v16f acc;
; #pragma unroll
;             for (int r = 0; r < 16; ++r) acc[r] = 0.f;
; #pragma unroll
;             for (int ks = 0; ks < 8; ++ks) {
;                 const bfx8 va = *(const LAS bfx8*)(VT + (32 * db + tl) * VT_STRIDE + 16 * ks + 8 * hh);
;                 acc = __builtin_amdgcn_mfma_f32_32x32x16_bf16(va, wf[ks], acc, 0, 0, 0);
;             }
; #pragma unroll
;             for (int rg = 0; rg < 4; ++rg) {
;                 const v2u u2 = uw[dbi][rg];
;                 const float o0 = bf_lo(u2.x) * (acc[4 * rg + 0] + bias), o1 = bf_hi(u2.x) * (acc[4 * rg + 1] + bias);
;                 const float o2 = bf_lo(u2.y) * (acc[4 * rg + 2] + bias), o3 = bf_hi(u2.y) * (acc[4 * rg + 3] + bias);
;                 ssq += (o0 * o0 + o1 * o1) + (o2 * o2 + o3 * o3);
;                 outp[h][dbi][2 * rg] = cvt_pk_nv(o0, o1); outp[h][dbi][2 * rg + 1] = cvt_pk_nv(o2, o3);
;             }
	v_mfma_f32_32x32x16_bf16 v[0:15], v[4:7], v[0:3], 0
	v_cvt_pk_bf16_f32 v134, v75, v101
	v_lshlrev_b32_e32 v75, 16, v72
	v_add_f32_e32 v16, v128, v16
	v_mul_f32_e32 v75, v16, v75
	v_and_b32_e32 v16, 0xffff0000, v72
	v_add_f32_e32 v17, v128, v17
	v_mul_f32_e32 v72, v17, v16
	v_mfma_f32_32x32x16_bf16 v[0:15], v[114:117], v[64:67], v[0:15]
	ds_read_b128 v[64:67], v102 offset:8800
	v_lshlrev_b32_e32 v16, 16, v73
	v_add_f32_e32 v17, v128, v18
	v_mul_f32_e32 v101, v17, v16
	v_and_b32_e32 v16, 0xffff0000, v73
	v_add_f32_e32 v17, v128, v19
	v_add_f32_e32 v74, v74, v111
	v_mfma_f32_32x32x16_bf16 v[0:15], v[118:121], v[60:63], v[0:15]
	v_mul_f32_e32 v60, v17, v16
	ds_read_b128 v[16:19], v102 offset:8832
	v_mul_f32_e32 v61, v72, v72
	v_mul_f32_e32 v62, v60, v60
	v_fmac_f32_e32 v61, v75, v75
	v_fmac_f32_e32 v62, v101, v101
	v_cvt_pk_bf16_f32 v135, v101, v60
	s_waitcnt lgkmcnt(1)
	v_mfma_f32_32x32x16_bf16 v[0:15], v[64:67], v[56:59], v[0:15]
	v_add_f32_e32 v56, v61, v62
	v_add_f32_e32 v61, v56, v74
	ds_read_b128 v[56:59], v102 offset:8864
	v_lshlrev_b32_e32 v60, 16, v70
	v_cvt_pk_bf16_f32 v133, v103, v110
	v_cvt_pk_bf16_f32 v136, v75, v72
	v_and_b32_e32 v130, 0xffff0000, v25
	s_waitcnt lgkmcnt(1)
	v_mfma_f32_32x32x16_bf16 v[0:15], v[16:19], v[48:51], v[0:15]
	v_add_f32_e32 v16, v128, v20
	v_mul_f32_e32 v48, v16, v60
	v_and_b32_e32 v16, 0xffff0000, v70
	v_add_f32_e32 v17, v128, v21
	v_mul_f32_e32 v49, v17, v16
	ds_read_b128 v[16:19], v102 offset:8896
	v_lshlrev_b32_e32 v20, 16, v71
	s_waitcnt lgkmcnt(1)
	v_mfma_f32_32x32x16_bf16 v[0:15], v[56:59], v[44:47], v[0:15]
	v_add_f32_e32 v21, v128, v22
	v_mul_f32_e32 v44, v21, v20
	v_and_b32_e32 v20, 0xffff0000, v71
	v_add_f32_e32 v21, v128, v23
	v_mul_f32_e32 v45, v21, v20
	ds_read_b128 v[20:23], v102 offset:8928
	v_mul_f32_e32 v46, v49, v49
	s_waitcnt lgkmcnt(1)
	v_mfma_f32_32x32x16_bf16 v[0:15], v[16:19], v[36:39], v[0:15]
	v_lshlrev_b32_e32 v17, 16, v68
	v_mul_f32_e32 v16, v45, v45
	v_fmac_f32_e32 v46, v48, v48
	v_fmac_f32_e32 v16, v44, v44
	v_add_f32_e32 v16, v46, v16
	v_add_f32_e32 v16, v16, v61
	v_cvt_pk_bf16_f32 v138, v48, v49
	s_waitcnt lgkmcnt(0)
	v_mfma_f32_32x32x16_bf16 v[0:15], v[20:23], v[28:31], v[0:15]
	v_cvt_pk_bf16_f32 v137, v44, v45
	v_lshlrev_b32_e32 v131, 16, v25
	v_and_b32_e32 v160, 0xffff0000, v26
	v_lshlrev_b32_e32 v161, 16, v26
	v_and_b32_e32 v162, 0xffff0000, v27
	v_lshlrev_b32_e32 v163, 16, v27
	v_lshlrev_b32_e32 v60, 16, v113
	s_nop 5
	v_add_f32_e32 v0, v128, v0
	v_mul_f32_e32 v0, v0, v17
	v_and_b32_e32 v17, 0xffff0000, v68
	v_add_f32_e32 v1, v128, v1
	v_mul_f32_e32 v1, v1, v17
	v_lshlrev_b32_e32 v17, 16, v69
	v_add_f32_e32 v2, v128, v2
	v_mul_f32_e32 v2, v2, v17
	v_and_b32_e32 v17, 0xffff0000, v69
	v_add_f32_e32 v3, v128, v3
	v_mul_f32_e32 v3, v3, v17
	v_mul_f32_e32 v17, v1, v1
	v_mul_f32_e32 v18, v3, v3
	v_fmac_f32_e32 v17, v0, v0
	v_fmac_f32_e32 v18, v2, v2
	v_add_f32_e32 v17, v17, v18
	v_add_f32_e32 v129, v16, v17
	v_add_co_u32_e32 v16, vcc, s39, v104
	v_cvt_pk_bf16_f32 v103, v0, v1
	v_cvt_pk_bf16_f32 v101, v2, v3
	v_add_f32_e32 v4, v128, v4
	s_nop 0
	v_addc_co_u32_e32 v17, vcc, 0, v105, vcc
	global_load_dwordx4 v[0:3], v[16:17], off offset:-3584
	global_load_dwordx4 v[72:75], v[16:17], off offset:-2560
	global_load_dwordx4 v[68:71], v[16:17], off offset:-1536
	global_load_dwordx4 v[64:67], v[16:17], off offset:-512
	global_load_dwordx4 v[56:59], v[16:17], off offset:512
	global_load_dwordx4 v[48:51], v[16:17], off offset:1536
	global_load_dwordx4 v[44:47], v[16:17], off offset:2560
	global_load_dwordx4 v[36:39], v[16:17], off offset:3584
	global_load_dwordx4 v[238:241], v[236:237], off offset:256
	global_load_dwordx4 v[242:245], v[236:237], off offset:288
	global_load_dwordx4 v[246:249], v[236:237], off offset:320
	global_load_dwordx4 v[250:253], v[236:237], off offset:352
	s_load_dwordx2 s[0:1], s[0:1], 0x68
	v_lshlrev_b32_e32 v16, 16, v112
	v_mul_f32_e32 v157, v4, v16
	v_and_b32_e32 v4, 0xffff0000, v112
	v_add_f32_e32 v5, v128, v5
	s_waitcnt lgkmcnt(0)
	global_load_dword v159, v156, s[0:1] offset:512
	s_mov_b64 s[0:1], s[80:81]
	s_load_dwordx2 s[28:29], s[0:1], 0x58
	s_waitcnt lgkmcnt(0)
	global_load_dwordx4 v[16:19], v139, s[28:29] offset:560
	global_load_dwordx4 v[20:23], v139, s[28:29] offset:544
	global_load_dwordx4 v[28:31], v139, s[28:29] offset:528
	global_load_dwordx4 v[140:143], v139, s[28:29] offset:512
	v_mul_f32_e32 v112, v5, v4
	v_and_b32_e32 v4, 0xffff0000, v24
	v_lshlrev_b32_e32 v5, 16, v24
	v_pk_mul_f32 v[32:33], v[4:5], v[4:5]
	v_add_f32_e32 v6, v128, v6
	v_add_f32_e32 v24, v33, v34
	v_add_f32_e32 v32, v32, v24
	v_pk_mul_f32 v[24:25], v[130:131], v[130:131]
	v_mul_f32_e32 v204, v6, v60
	v_add_f32_e32 v25, v25, v32
	v_add_f32_e32 v32, v24, v25
	v_pk_mul_f32 v[24:25], v[160:161], v[160:161]
	v_and_b32_e32 v6, 0xffff0000, v113
	v_add_f32_e32 v25, v25, v32
	v_add_f32_e32 v26, v24, v25
	v_pk_mul_f32 v[24:25], v[162:163], v[162:163]
	v_add_f32_e32 v8, v128, v8
	v_add_f32_e32 v25, v25, v26
	v_add_f32_e32 v32, v24, v25
	global_load_dwordx4 v[24:27], v139, s[28:29] offset:624
	global_load_dwordx4 v[144:147], v139, s[28:29] offset:608
	global_load_dwordx4 v[148:151], v139, s[28:29] offset:592
	global_load_dwordx4 v[152:155], v139, s[28:29] offset:576
	ds_bpermute_b32 v33, v183, v32
	s_waitcnt lgkmcnt(0)
	s_barrier
; __device__ __forceinline__ float bf_lo(unsigned w) { return __uint_as_float(w << 16); }
; __device__ __forceinline__ float bf_hi(unsigned w) { return __uint_as_float(w & 0xffff0000u); }
; __device__ __forceinline__ bf16 f2bf(float f) { return (bf16)(cvt_pk_nv(f, 0.f) & 0xffffu); }
; __device__ __forceinline__ void gmlp_tile(const Ctx& C, int T, LAS unsigned char* lds, int wave, int lane, int tid) {
;     ...
;         __syncthreads();
;         {
;             float v[32]; float s = 0.f;
; #pragma unroll
;             for (int i = 0; i < 4; ++i) { const v4u w = vraw[i];
;                 v[8 * i + 0] = bf_lo(w.x); v[8 * i + 1] = bf_hi(w.x); v[8 * i + 2] = bf_lo(w.y); v[8 * i + 3] = bf_hi(w.y);
;                 v[8 * i + 4] = bf_lo(w.z); v[8 * i + 5] = bf_hi(w.z); v[8 * i + 6] = bf_lo(w.w); v[8 * i + 7] = bf_hi(w.w); }
;             if (h < 3) {
; #pragma unroll
;                 for (int i = 0; i < 4; ++i) vraw[i] = *(const v4u*)(vsrc + (h + 1) * 128 + 8 * i);
;             }
; #pragma unroll
;             for (int i = 0; i < 32; ++i) s += v[i] * v[i];
;             s += __shfl_xor(s, 1); s += __shfl_xor(s, 2);
;             const float r = rsqrtf(s * (1.f / 128.f) + EPS);
; #pragma unroll
;             for (int i = 0; i < 32; ++i) { v[i] = v[i] * r * gvv[i >> 2][i & 3]; VT[(q * 32 + i) * VT_STRIDE + row] = f2bf(v[i]); }
	s_mov_b64 s[0:1], s[80:81]
	v_add_f32_e32 v32, v32, v33
	ds_bpermute_b32 v33, v184, v32
	s_waitcnt lgkmcnt(0)
	v_add_f32_e32 v32, v32, v33
	v_fmamk_f32 v32, v32, 0x3c000000, v177
	v_mul_f32_e32 v33, 0x4b800000, v32
	v_cmp_gt_f32_e32 vcc, s38, v32
	s_nop 1
	v_cndmask_b32_e32 v32, v32, v33, vcc
	v_rsq_f32_e32 v113, v32
	global_load_dwordx4 v[32:35], v[108:109], off offset:560
	global_load_dwordx4 v[40:43], v[108:109], off offset:544
	global_load_dwordx4 v[52:55], v[108:109], off offset:528
	global_load_dwordx4 v[60:63], v[108:109], off offset:512
	v_mul_f32_e32 v205, 0x45800000, v113
	v_cndmask_b32_e32 v113, v113, v205, vcc
	v_mul_f32_e32 v158, v113, v158
	v_mul_f32_e32 v4, v113, v4
	v_mul_f32_e32 v5, v113, v5
	s_waitcnt vmcnt(8)
	v_permlane32_swap_b32_e32 v238, v240
	v_permlane32_swap_b32_e32 v239, v241
	v_permlane32_swap_b32_e32 v242, v244
	v_permlane32_swap_b32_e32 v243, v245
	v_permlane32_swap_b32_e32 v246, v248
	v_permlane32_swap_b32_e32 v247, v249
	v_permlane32_swap_b32_e32 v250, v252
	v_permlane32_swap_b32_e32 v251, v253
	v_mov_b32_e32 v126, v238
	v_mov_b32_e32 v127, v239
	v_mov_b32_e32 v124, v240
	v_mov_b32_e32 v125, v241
	v_mov_b32_e32 v122, v242
	v_mov_b32_e32 v123, v243
	v_mov_b32_e32 v118, v244
	v_mov_b32_e32 v119, v245
	v_mov_b32_e32 v116, v246
	v_mov_b32_e32 v117, v247
	v_mov_b32_e32 v120, v248
	v_mov_b32_e32 v121, v249
	v_mov_b32_e32 v114, v250
	v_mov_b32_e32 v115, v251
	v_mov_b32_e32 v110, v252
	v_mov_b32_e32 v111, v253
	v_mul_f32_e32 v140, v140, v158
	v_cvt_pk_bf16_f32 v140, v140, v83
	ds_write_b16 v174, v140
	v_mul_f32_e32 v140, v113, v164
	v_mul_f32_e32 v140, v141, v140
	v_cvt_pk_bf16_f32 v140, v140, v83
	ds_write_b16 v174, v140 offset:272
	v_mul_f32_e32 v140, v113, v165
	v_mul_f32_e32 v140, v142, v140
	v_cvt_pk_bf16_f32 v140, v140, v83
	ds_write_b16 v174, v140 offset:544
	v_mul_f32_e32 v140, v113, v166
	v_mul_f32_e32 v140, v143, v140
	v_cvt_pk_bf16_f32 v140, v140, v83
	ds_write_b16 v174, v140 offset:816
	v_mul_f32_e32 v140, v113, v167
	v_mul_f32_e32 v28, v28, v140
	v_cvt_pk_bf16_f32 v28, v28, v83
	ds_write_b16 v174, v28 offset:1088
	v_mul_f32_e32 v28, v113, v178
	v_mul_f32_e32 v28, v29, v28
	v_cvt_pk_bf16_f32 v28, v28, v83
	ds_write_b16 v174, v28 offset:1360
	v_mul_f32_e32 v28, v113, v179
	v_mul_f32_e32 v28, v30, v28
	v_cvt_pk_bf16_f32 v28, v28, v83
	ds_write_b16 v174, v28 offset:1632
	v_mul_f32_e32 v28, v113, v180
	v_mul_f32_e32 v28, v31, v28
	v_cvt_pk_bf16_f32 v28, v28, v83
	ds_write_b16 v174, v28 offset:1904
	v_mul_f32_e32 v28, v113, v181
	v_mul_f32_e32 v20, v20, v28
	v_cvt_pk_bf16_f32 v20, v20, v83
	ds_write_b16 v174, v20 offset:2176
	v_mul_f32_e32 v20, v113, v189
	v_mul_f32_e32 v20, v21, v20
	v_cvt_pk_bf16_f32 v20, v20, v83
	ds_write_b16 v174, v20 offset:2448
	v_mul_f32_e32 v20, v113, v190
	v_mul_f32_e32 v20, v22, v20
	v_cvt_pk_bf16_f32 v20, v20, v83
	ds_write_b16 v174, v20 offset:2720
	v_mul_f32_e32 v20, v113, v191
	v_mul_f32_e32 v20, v23, v20
	v_cvt_pk_bf16_f32 v20, v20, v83
	ds_write_b16 v174, v20 offset:2992
	v_mul_f32_e32 v20, v113, v192
	v_mul_f32_e32 v16, v16, v20
	v_cvt_pk_bf16_f32 v16, v16, v83
	ds_write_b16 v174, v16 offset:3264
	v_mul_f32_e32 v16, v113, v193
	v_mul_f32_e32 v16, v17, v16
	v_cvt_pk_bf16_f32 v16, v16, v83
	ds_write_b16 v174, v16 offset:3536
	v_mul_f32_e32 v16, v113, v194
	v_mul_f32_e32 v16, v18, v16
	v_cvt_pk_bf16_f32 v16, v16, v83
	ds_write_b16 v174, v16 offset:3808
	v_mul_f32_e32 v16, v113, v195
	v_mul_f32_e32 v16, v19, v16
	v_cvt_pk_bf16_f32 v16, v16, v83
	ds_write_b16 v174, v16 offset:4080
	v_mul_f32_e32 v16, v113, v196
	s_waitcnt vmcnt(4)
	v_mul_f32_e32 v16, v152, v16
	v_cvt_pk_bf16_f32 v16, v16, v83
	ds_write_b16 v174, v16 offset:4352
	v_mul_f32_e32 v16, v113, v197
	v_mul_f32_e32 v16, v153, v16
	v_cvt_pk_bf16_f32 v16, v16, v83
	v_mul_f32_e32 v4, v145, v4
	ds_write_b16 v174, v16 offset:4624
	v_mul_f32_e32 v16, v113, v198
	v_cvt_pk_bf16_f32 v4, v4, v83
	v_mul_f32_e32 v16, v154, v16
	ds_write_b16 v174, v4 offset:6800
	v_mul_f32_e32 v4, v113, v131
	v_cvt_pk_bf16_f32 v16, v16, v83
	v_mul_f32_e32 v4, v146, v4
	ds_write_b16 v174, v16 offset:4896
	v_mul_f32_e32 v16, v113, v199
	v_cvt_pk_bf16_f32 v4, v4, v83
	v_mul_f32_e32 v16, v155, v16
	ds_write_b16 v174, v4 offset:7072
	v_mul_f32_e32 v4, v113, v130
	v_cvt_pk_bf16_f32 v16, v16, v83
	v_mul_f32_e32 v4, v147, v4
	ds_write_b16 v174, v16 offset:5168
	v_mul_f32_e32 v16, v113, v200
	v_cvt_pk_bf16_f32 v4, v4, v83
	v_mul_f32_e32 v16, v148, v16
	ds_write_b16 v174, v4 offset:7344
	v_mul_f32_e32 v4, v113, v161
	v_cvt_pk_bf16_f32 v16, v16, v83
	v_mul_f32_e32 v4, v24, v4
	ds_write_b16 v174, v16 offset:5440
	v_mul_f32_e32 v16, v113, v201
	v_cvt_pk_bf16_f32 v4, v4, v83
	v_mul_f32_e32 v16, v149, v16
	ds_write_b16 v174, v4 offset:7616
	v_mul_f32_e32 v4, v113, v160
	v_cvt_pk_bf16_f32 v16, v16, v83
	v_mul_f32_e32 v4, v25, v4
	ds_write_b16 v174, v16 offset:5712
	v_mul_f32_e32 v16, v113, v202
	v_cvt_pk_bf16_f32 v4, v4, v83
	v_mul_f32_e32 v16, v150, v16
	ds_write_b16 v174, v4 offset:7888
	v_mul_f32_e32 v4, v113, v163
	v_cvt_pk_bf16_f32 v16, v16, v83
	v_mul_f32_e32 v4, v26, v4
	ds_write_b16 v174, v16 offset:5984
	v_mul_f32_e32 v16, v113, v203
	v_cvt_pk_bf16_f32 v4, v4, v83
	v_mul_f32_e32 v16, v151, v16
	ds_write_b16 v174, v4 offset:8160
	v_mul_f32_e32 v4, v113, v162
	v_cvt_pk_bf16_f32 v16, v16, v83
	v_mul_f32_e32 v5, v144, v5
	v_mul_f32_e32 v4, v27, v4
	ds_write_b16 v174, v16 offset:6256
	v_cvt_pk_bf16_f32 v5, v5, v83
	ds_write_b16 v174, v5 offset:6528
	v_cvt_pk_bf16_f32 v4, v4, v83
	ds_write_b16 v174, v4 offset:8432
	s_waitcnt lgkmcnt(0)
	s_barrier
; __device__ __forceinline__ float bf_lo(unsigned w) { return __uint_as_float(w << 16); }
; __device__ __forceinline__ float bf_hi(unsigned w) { return __uint_as_float(w & 0xffff0000u); }
; #define LAS __attribute__((address_space(3)))
; __device__ __forceinline__ unsigned cvt_pk_nv(float lo, float hi) { unsigned r; asm("v_cvt_pk_bf16_f32 %0, %1, %2" : "=v"(r) : "v"(lo), "v"(hi)); return r; }
; __device__ __forceinline__ void gmlp_tile(const Ctx& C, int T, LAS unsigned char* lds, int wave, int lane, int tid) {
;     ...
; #pragma unroll
;         for (int dbi = 0; dbi < 2; ++dbi) {
;             const int db = 2 * dh + dbi;
;             v16f acc;
; #pragma unroll
;             for (int r = 0; r < 16; ++r) acc[r] = 0.f;
; #pragma unroll
;             for (int ks = 0; ks < 8; ++ks) {
;                 const bfx8 va = *(const LAS bfx8*)(VT + (32 * db + tl) * VT_STRIDE + 16 * ks + 8 * hh);
;                 acc = __builtin_amdgcn_mfma_f32_32x32x16_bf16(va, wf[ks], acc, 0, 0, 0);
;             }
; #pragma unroll
;             for (int rg = 0; rg < 4; ++rg) {
;                 const v2u u2 = uw[dbi][rg];
;                 const float o0 = bf_lo(u2.x) * (acc[4 * rg + 0] + bias), o1 = bf_hi(u2.x) * (acc[4 * rg + 1] + bias);
;                 const float o2 = bf_lo(u2.y) * (acc[4 * rg + 2] + bias), o3 = bf_hi(u2.y) * (acc[4 * rg + 3] + bias);
;                 ssq += (o0 * o0 + o1 * o1) + (o2 * o2 + o3 * o3);
;                 outp[h][dbi][2 * rg] = cvt_pk_nv(o0, o1); outp[h][dbi][2 * rg + 1] = cvt_pk_nv(o2, o3);
;             }
	ds_read_b128 v[16:19], v102
	v_add_f32_e32 v4, v128, v7
	v_mul_f32_e32 v113, v4, v6
	v_mul_f32_e32 v4, v112, v112
	v_mul_f32_e32 v5, v113, v113
	v_fmac_f32_e32 v4, v157, v157
	v_fmac_f32_e32 v5, v204, v204
	v_add_f32_e32 v130, v4, v5
	ds_read_b128 v[4:7], v102 offset:32
	s_waitcnt lgkmcnt(1)
	v_mfma_f32_32x32x16_bf16 v[16:31], v[16:19], v[0:3], 0
	ds_read_b128 v[146:149], v102 offset:64
	v_cvt_pk_bf16_f32 v145, v157, v112
	v_lshlrev_b32_e32 v112, 16, v78
	v_cvt_pk_bf16_f32 v142, v204, v113
	v_mul_f32_e32 v112, v8, v112
	v_and_b32_e32 v8, 0xffff0000, v79
	v_add_f32_e32 v129, v130, v129
	s_waitcnt lgkmcnt(1)
	v_mfma_f32_32x32x16_bf16 v[16:31], v[4:7], v[72:75], v[16:31]
	v_and_b32_e32 v4, 0xffff0000, v78
	v_add_f32_e32 v5, v128, v9
	v_mul_f32_e32 v78, v5, v4
	v_lshlrev_b32_e32 v4, 16, v79
	v_add_f32_e32 v5, v128, v10
	v_mul_f32_e32 v113, v5, v4
	ds_read_b128 v[4:7], v102 offset:96
	s_waitcnt lgkmcnt(1)
	v_mfma_f32_32x32x16_bf16 v[16:31], v[146:149], v[68:71], v[16:31]
	v_add_f32_e32 v9, v128, v11
	v_mul_f32_e32 v79, v9, v8
	ds_read_b128 v[8:11], v102 offset:128
	v_mul_f32_e32 v130, v78, v78
	v_mul_f32_e32 v131, v79, v79
	v_fmac_f32_e32 v130, v112, v112
	v_fmac_f32_e32 v131, v113, v113
	s_waitcnt lgkmcnt(1)
	v_mfma_f32_32x32x16_bf16 v[16:31], v[4:7], v[64:67], v[16:31]
	v_add_f32_e32 v4, v130, v131
	v_add_f32_e32 v129, v4, v129
	ds_read_b128 v[4:7], v102 offset:160
	v_cvt_pk_bf16_f32 v146, v112, v78
	v_lshlrev_b32_e32 v78, 16, v76
	v_cvt_pk_bf16_f32 v143, v113, v79
	s_waitcnt vmcnt(0)
	v_and_b32_e32 v189, 0xffff0000, v60
	s_waitcnt lgkmcnt(1)
	v_mfma_f32_32x32x16_bf16 v[16:31], v[8:11], v[56:59], v[16:31]
	v_add_f32_e32 v8, v128, v12
	v_mul_f32_e32 v12, v8, v78
	v_and_b32_e32 v8, 0xffff0000, v76
	v_add_f32_e32 v9, v128, v13
	v_mul_f32_e32 v13, v9, v8
	ds_read_b128 v[8:11], v102 offset:192
	v_lshlrev_b32_e32 v76, 16, v77
	s_waitcnt lgkmcnt(1)
	v_mfma_f32_32x32x16_bf16 v[16:31], v[4:7], v[48:51], v[16:31]
	v_add_f32_e32 v4, v128, v14
	v_mul_f32_e32 v14, v4, v76
	v_and_b32_e32 v4, 0xffff0000, v77
	v_add_f32_e32 v5, v128, v15
	v_mul_f32_e32 v15, v5, v4
	ds_read_b128 v[4:7], v102 offset:224
	v_mul_f32_e32 v76, v13, v13
	s_waitcnt lgkmcnt(1)
	v_mfma_f32_32x32x16_bf16 v[16:31], v[8:11], v[44:47], v[16:31]
	v_mul_f32_e32 v8, v15, v15
	v_fmac_f32_e32 v76, v12, v12
	v_fmac_f32_e32 v8, v14, v14
	v_add_f32_e32 v8, v76, v8
	v_add_f32_e32 v8, v8, v129
	v_cvt_pk_bf16_f32 v147, v12, v13
	v_cvt_pk_bf16_f32 v144, v14, v15
	s_waitcnt lgkmcnt(0)
	v_mfma_f32_32x32x16_bf16 v[16:31], v[4:7], v[36:39], v[16:31]
	v_lshlrev_b32_e32 v4, 16, v126
	v_lshlrev_b32_e32 v162, 16, v60
	v_lshlrev_b32_e32 v198, 16, v61
	v_and_b32_e32 v199, 0xffff0000, v61
	v_lshlrev_b32_e32 v200, 16, v62
	v_and_b32_e32 v201, 0xffff0000, v62
	v_lshlrev_b32_e32 v202, 16, v63
	s_nop 4
	v_add_f32_e32 v5, v159, v16
	v_mul_f32_e32 v4, v5, v4
	v_and_b32_e32 v5, 0xffff0000, v126
	v_add_f32_e32 v6, v159, v17
	v_mul_f32_e32 v5, v6, v5
	v_lshlrev_b32_e32 v6, 16, v127
	v_add_f32_e32 v7, v159, v18
	v_mul_f32_e32 v6, v7, v6
	v_and_b32_e32 v7, 0xffff0000, v127
	v_add_f32_e32 v9, v159, v19
	v_mul_f32_e32 v7, v9, v7
	v_mul_f32_e32 v9, v5, v5
	v_fmac_f32_e32 v9, v4, v4
	v_cvt_pk_bf16_f32 v141, v4, v5
	v_lshlrev_b32_e32 v4, 16, v124
	v_add_f32_e32 v5, v159, v20
	v_mul_f32_e32 v20, v5, v4
	v_and_b32_e32 v4, 0xffff0000, v124
	v_add_f32_e32 v5, v159, v21
	v_mul_f32_e32 v10, v7, v7
	v_mul_f32_e32 v21, v5, v4
	v_lshlrev_b32_e32 v4, 16, v125
	v_add_f32_e32 v5, v159, v22
	v_fmac_f32_e32 v10, v6, v6
	v_cvt_pk_bf16_f32 v140, v6, v7
	v_mul_f32_e32 v22, v5, v4
	ds_read_b128 v[4:7], v102 offset:8704
	ds_read_b128 v[16:19], v102 offset:8736
	v_add_f32_e32 v9, v9, v10
	v_add_f32_e32 v76, v8, v9
	v_and_b32_e32 v8, 0xffff0000, v125
	v_add_f32_e32 v9, v159, v23
	v_mul_f32_e32 v23, v9, v8
	v_mul_f32_e32 v8, v21, v21
	v_mul_f32_e32 v9, v23, v23
	v_fmac_f32_e32 v8, v20, v20
	v_fmac_f32_e32 v9, v22, v22
	v_add_f32_e32 v77, v8, v9
	s_waitcnt lgkmcnt(1)
	v_mfma_f32_32x32x16_bf16 v[0:15], v[4:7], v[0:3], 0
	v_cvt_pk_bf16_f32 v153, v20, v21
	v_lshlrev_b32_e32 v20, 16, v122
	v_add_f32_e32 v21, v159, v24
	v_cvt_pk_bf16_f32 v150, v22, v23
	v_mul_f32_e32 v24, v21, v20
	ds_read_b128 v[20:23], v102 offset:8768
	v_add_f32_e32 v76, v77, v76
	s_waitcnt lgkmcnt(1)
	v_mfma_f32_32x32x16_bf16 v[0:15], v[16:19], v[72:75], v[0:15]
	v_and_b32_e32 v16, 0xffff0000, v122
	v_add_f32_e32 v17, v159, v25
	v_mul_f32_e32 v25, v17, v16
	v_lshlrev_b32_e32 v16, 16, v123
	v_add_f32_e32 v17, v159, v26
	v_mul_f32_e32 v26, v17, v16
	ds_read_b128 v[16:19], v102 offset:8800
	s_waitcnt lgkmcnt(1)
	v_mfma_f32_32x32x16_bf16 v[0:15], v[20:23], v[68:71], v[0:15]
	v_and_b32_e32 v20, 0xffff0000, v123
	v_add_f32_e32 v21, v159, v27
	v_mul_f32_e32 v27, v21, v20
	ds_read_b128 v[20:23], v102 offset:8832
	v_mul_f32_e32 v68, v25, v25
	v_mul_f32_e32 v69, v27, v27
	v_fmac_f32_e32 v68, v24, v24
	s_waitcnt lgkmcnt(1)
	v_mfma_f32_32x32x16_bf16 v[0:15], v[16:19], v[64:67], v[0:15]
	v_fmac_f32_e32 v69, v26, v26
	v_add_f32_e32 v16, v68, v69
	v_add_f32_e32 v64, v16, v76
	ds_read_b128 v[16:19], v102 offset:8864
	v_cvt_pk_bf16_f32 v154, v24, v25
	v_lshlrev_b32_e32 v24, 16, v118
	v_cvt_pk_bf16_f32 v151, v26, v27
	s_waitcnt lgkmcnt(1)
	v_mfma_f32_32x32x16_bf16 v[0:15], v[20:23], v[56:59], v[0:15]
	v_add_f32_e32 v20, v159, v28
	v_mul_f32_e32 v24, v20, v24
	v_and_b32_e32 v20, 0xffff0000, v118
	v_add_f32_e32 v21, v159, v29
	v_mul_f32_e32 v25, v21, v20
	ds_read_b128 v[20:23], v102 offset:8896
	v_lshlrev_b32_e32 v26, 16, v119
	s_waitcnt lgkmcnt(1)
; __device__ __forceinline__ float bf_lo(unsigned w) { return __uint_as_float(w << 16); }
; __device__ __forceinline__ float bf_hi(unsigned w) { return __uint_as_float(w & 0xffff0000u); }
;     __device__ __forceinline__ const float* in(int i) const { return karg_in(i); }
; __device__ __forceinline__ void gmlp_tile(const Ctx& C, int T, LAS unsigned char* lds, int wave, int lane, int tid) {
;     ...
;         const bf16* wrow = Weff + ((size_t)(mode * 4 + h) * 128 + t) * 128 + 8 * hh;
; #pragma unroll
;         for (int ks = 0; ks < 8; ++ks) wf[ks] = *(const bfx8*)(wrow + 16 * ks);
;         v2u uw[2][4];
; #pragma unroll
;         for (int dbi = 0; dbi < 2; ++dbi)
; #pragma unroll
;             for (int rg = 0; rg < 4; ++rg) uw[dbi][rg] = *(const v2u*)(zt + h * 128 + 32 * (2 * dh + dbi) + 8 * rg + 4 * hh);
;         const float bias = C.in(13)[h * 128 + (mode ? (t & 15) : t)];
;         v4f gvv[8];
;         { const float* gvp = C.in(11) + h * 128 + q * 32;
; #pragma unroll
;           for (int i = 0; i < 8; ++i) gvv[i] = *(const v4f*)(gvp + 4 * i); }
;         __syncthreads();
;         {
;             float v[32]; float s = 0.f;
; #pragma unroll
;             for (int i = 0; i < 4; ++i) { const v4u w = vraw[i];
;                 v[8 * i + 0] = bf_lo(w.x); v[8 * i + 1] = bf_hi(w.x); v[8 * i + 2] = bf_lo(w.y); v[8 * i + 3] = bf_hi(w.y);
;                 v[8 * i + 4] = bf_lo(w.z); v[8 * i + 5] = bf_hi(w.z); v[8 * i + 6] = bf_lo(w.w); v[8 * i + 7] = bf_hi(w.w); }
;             if (h < 3) {
; #pragma unroll
;                 for (int i = 0; i < 4; ++i) vraw[i] = *(const v4u*)(vsrc + (h + 1) * 128 + 8 * i);
;             }
; #pragma unroll
;             for (int i = 0; i < 32; ++i) s += v[i] * v[i];
	v_mfma_f32_32x32x16_bf16 v[0:15], v[16:19], v[48:51], v[0:15]
	v_add_f32_e32 v16, v159, v30
	v_mul_f32_e32 v26, v16, v26
	v_and_b32_e32 v16, 0xffff0000, v119
	v_add_f32_e32 v17, v159, v31
	v_mul_f32_e32 v27, v17, v16
	ds_read_b128 v[16:19], v102 offset:8928
	v_mul_f32_e32 v28, v25, v25
	s_waitcnt lgkmcnt(1)
	v_mfma_f32_32x32x16_bf16 v[0:15], v[20:23], v[44:47], v[0:15]
	v_mul_f32_e32 v20, v27, v27
	v_fmac_f32_e32 v28, v24, v24
	v_fmac_f32_e32 v20, v26, v26
	v_add_f32_e32 v20, v28, v20
	v_add_f32_e32 v20, v20, v64
	v_cvt_pk_bf16_f32 v155, v24, v25
	v_cvt_pk_bf16_f32 v152, v26, v27
	s_waitcnt lgkmcnt(0)
	v_mfma_f32_32x32x16_bf16 v[0:15], v[16:19], v[36:39], v[0:15]
	v_lshlrev_b32_e32 v16, 16, v116
	v_mul_f32_e32 v39, v189, v189
	v_fmac_f32_e32 v39, v162, v162
	v_fmac_f32_e32 v39, v198, v198
	v_fmac_f32_e32 v39, v199, v199
	v_fmac_f32_e32 v39, v200, v200
	v_fmac_f32_e32 v39, v201, v201
	s_nop 4
	v_add_f32_e32 v0, v159, v0
	v_mul_f32_e32 v0, v0, v16
	v_and_b32_e32 v16, 0xffff0000, v116
	v_add_f32_e32 v1, v159, v1
	v_mul_f32_e32 v1, v1, v16
	v_lshlrev_b32_e32 v16, 16, v117
	v_add_f32_e32 v2, v159, v2
	v_mul_f32_e32 v2, v2, v16
	v_and_b32_e32 v16, 0xffff0000, v117
	v_add_f32_e32 v3, v159, v3
	v_mul_f32_e32 v3, v3, v16
	v_mul_f32_e32 v16, v1, v1
	v_mul_f32_e32 v17, v3, v3
	v_fmac_f32_e32 v16, v0, v0
	v_fmac_f32_e32 v17, v2, v2
	v_add_f32_e32 v16, v16, v17
	v_add_f32_e32 v157, v20, v16
	v_add_co_u32_e32 v16, vcc, s40, v104
	v_cvt_pk_bf16_f32 v149, v0, v1
	v_cvt_pk_bf16_f32 v148, v2, v3
	v_add_f32_e32 v4, v159, v4
	s_nop 0
	v_addc_co_u32_e32 v17, vcc, 0, v105, vcc
	global_load_dwordx4 v[0:3], v[16:17], off offset:-3584
	global_load_dwordx4 v[76:79], v[16:17], off offset:-2560
	global_load_dwordx4 v[72:75], v[16:17], off offset:-1536
	global_load_dwordx4 v[68:71], v[16:17], off offset:-512
	global_load_dwordx4 v[64:67], v[16:17], off offset:512
	global_load_dwordx4 v[56:59], v[16:17], off offset:1536
	global_load_dwordx4 v[48:51], v[16:17], off offset:2560
	global_load_dwordx4 v[44:47], v[16:17], off offset:3584
	global_load_dwordx4 v[238:241], v[236:237], off offset:512
	global_load_dwordx4 v[242:245], v[236:237], off offset:544
	global_load_dwordx4 v[246:249], v[236:237], off offset:576
	global_load_dwordx4 v[250:253], v[236:237], off offset:608
	s_load_dwordx2 s[0:1], s[0:1], 0x68
	v_lshlrev_b32_e32 v16, 16, v120
	v_mul_f32_e32 v158, v4, v16
	v_and_b32_e32 v203, 0xffff0000, v63
	v_fmac_f32_e32 v39, v202, v202
	s_waitcnt lgkmcnt(0)
	global_load_dword v163, v156, s[0:1] offset:1024
	s_mov_b64 s[0:1], s[80:81]
	s_load_dwordx2 s[28:29], s[0:1], 0x58
	s_waitcnt lgkmcnt(0)
	global_load_dwordx4 v[16:19], v139, s[28:29] offset:1072
	global_load_dwordx4 v[20:23], v139, s[28:29] offset:1056
	global_load_dwordx4 v[24:27], v139, s[28:29] offset:1040
	global_load_dwordx4 v[28:31], v139, s[28:29] offset:1024
	v_lshlrev_b32_e32 v204, 16, v52
	v_fmac_f32_e32 v39, v203, v203
	v_and_b32_e32 v205, 0xffff0000, v52
	v_fmac_f32_e32 v39, v204, v204
	v_lshlrev_b32_e32 v206, 16, v53
	v_fmac_f32_e32 v39, v205, v205
	v_and_b32_e32 v207, 0xffff0000, v53
	v_fmac_f32_e32 v39, v206, v206
	v_lshlrev_b32_e32 v208, 16, v54
	v_fmac_f32_e32 v39, v207, v207
	v_and_b32_e32 v209, 0xffff0000, v54
	v_fmac_f32_e32 v39, v208, v208
	v_lshlrev_b32_e32 v210, 16, v55
	v_fmac_f32_e32 v39, v209, v209
	v_and_b32_e32 v211, 0xffff0000, v55
	v_fmac_f32_e32 v39, v210, v210
	v_lshlrev_b32_e32 v212, 16, v40
	v_fmac_f32_e32 v39, v211, v211
	v_and_b32_e32 v213, 0xffff0000, v40
	v_fmac_f32_e32 v39, v212, v212
	v_lshlrev_b32_e32 v214, 16, v41
	v_fmac_f32_e32 v39, v213, v213
	v_and_b32_e32 v215, 0xffff0000, v41
	v_fmac_f32_e32 v39, v214, v214
	v_lshlrev_b32_e32 v216, 16, v42
	v_fmac_f32_e32 v39, v215, v215
	v_and_b32_e32 v217, 0xffff0000, v42
	v_fmac_f32_e32 v39, v216, v216
	v_and_b32_e32 v4, 0xffff0000, v120
	v_add_f32_e32 v5, v159, v5
	v_lshlrev_b32_e32 v218, 16, v43
	v_fmac_f32_e32 v39, v217, v217
	v_mul_f32_e32 v120, v5, v4
	v_and_b32_e32 v219, 0xffff0000, v43
	v_fmac_f32_e32 v39, v218, v218
	v_and_b32_e32 v4, 0xffff0000, v32
	v_lshlrev_b32_e32 v5, 16, v32
	global_load_dwordx4 v[40:43], v139, s[28:29] offset:1136
	global_load_dwordx4 v[164:167], v139, s[28:29] offset:1120
	global_load_dwordx4 v[178:181], v139, s[28:29] offset:1104
	global_load_dwordx4 v[190:193], v139, s[28:29] offset:1088
	v_fmac_f32_e32 v39, v219, v219
	v_pk_mul_f32 v[36:37], v[4:5], v[4:5]
	v_and_b32_e32 v160, 0xffff0000, v33
	v_add_f32_e32 v32, v37, v39
	v_lshlrev_b32_e32 v161, 16, v33
	v_add_f32_e32 v36, v36, v32
	v_pk_mul_f32 v[32:33], v[160:161], v[160:161]
	v_and_b32_e32 v194, 0xffff0000, v34
	v_add_f32_e32 v33, v33, v36
	v_lshlrev_b32_e32 v195, 16, v34
	v_add_f32_e32 v36, v32, v33
	v_pk_mul_f32 v[32:33], v[194:195], v[194:195]
	v_and_b32_e32 v196, 0xffff0000, v35
	v_add_f32_e32 v33, v33, v36
	v_lshlrev_b32_e32 v197, 16, v35
	v_add_f32_e32 v34, v32, v33
	v_pk_mul_f32 v[32:33], v[196:197], v[196:197]
	v_lshlrev_b32_e32 v38, 16, v121
	v_add_f32_e32 v33, v33, v34
	v_add_f32_e32 v32, v32, v33
	ds_bpermute_b32 v33, v183, v32
	v_add_f32_e32 v6, v159, v6
	v_mul_f32_e32 v220, v6, v38
	v_and_b32_e32 v6, 0xffff0000, v121
	s_waitcnt lgkmcnt(0)
	v_add_f32_e32 v32, v32, v33
	ds_bpermute_b32 v33, v184, v32
	s_barrier
; __device__ __forceinline__ float bf_lo(unsigned w) { return __uint_as_float(w << 16); }
; __device__ __forceinline__ float bf_hi(unsigned w) { return __uint_as_float(w & 0xffff0000u); }
; __device__ __forceinline__ bf16 f2bf(float f) { return (bf16)(cvt_pk_nv(f, 0.f) & 0xffffu); }
; __device__ __forceinline__ void gmlp_tile(const Ctx& C, int T, LAS unsigned char* lds, int wave, int lane, int tid) {
;     ...
;         __syncthreads();
;         {
;             float v[32]; float s = 0.f;
; #pragma unroll
;             for (int i = 0; i < 4; ++i) { const v4u w = vraw[i];
;                 v[8 * i + 0] = bf_lo(w.x); v[8 * i + 1] = bf_hi(w.x); v[8 * i + 2] = bf_lo(w.y); v[8 * i + 3] = bf_hi(w.y);
;                 v[8 * i + 4] = bf_lo(w.z); v[8 * i + 5] = bf_hi(w.z); v[8 * i + 6] = bf_lo(w.w); v[8 * i + 7] = bf_hi(w.w); }
;             if (h < 3) {
; #pragma unroll
;                 for (int i = 0; i < 4; ++i) vraw[i] = *(const v4u*)(vsrc + (h + 1) * 128 + 8 * i);
;             }
; #pragma unroll
;             for (int i = 0; i < 32; ++i) s += v[i] * v[i];
;             s += __shfl_xor(s, 1); s += __shfl_xor(s, 2);
;             const float r = rsqrtf(s * (1.f / 128.f) + EPS);
; #pragma unroll
;             for (int i = 0; i < 32; ++i) { v[i] = v[i] * r * gvv[i >> 2][i & 3]; VT[(q * 32 + i) * VT_STRIDE + row] = f2bf(v[i]); }
	s_waitcnt lgkmcnt(0)
	v_add_f32_e32 v8, v159, v8
	s_mov_b64 s[0:1], s[80:81]
	v_add_f32_e32 v32, v32, v33
	v_fmamk_f32 v32, v32, 0x3c000000, v177
	v_mul_f32_e32 v33, 0x4b800000, v32
	v_cmp_gt_f32_e32 vcc, s38, v32
	s_nop 1
	v_cndmask_b32_e32 v32, v32, v33, vcc
	v_rsq_f32_e32 v121, v32
	global_load_dwordx4 v[36:39], v[108:109], off offset:768
	global_load_dwordx4 v[52:55], v[108:109], off offset:784
	global_load_dwordx4 v[32:35], v[108:109], off offset:816
	global_load_dwordx4 v[60:63], v[108:109], off offset:800
	v_mul_f32_e32 v108, 0x45800000, v121
	v_cndmask_b32_e32 v108, v121, v108, vcc
	v_mul_f32_e32 v109, v108, v162
	s_waitcnt vmcnt(8)
	v_permlane32_swap_b32_e32 v238, v240
	v_permlane32_swap_b32_e32 v239, v241
	v_permlane32_swap_b32_e32 v242, v244
	v_permlane32_swap_b32_e32 v243, v245
	v_permlane32_swap_b32_e32 v246, v248
	v_permlane32_swap_b32_e32 v247, v249
	v_permlane32_swap_b32_e32 v250, v252
	v_permlane32_swap_b32_e32 v251, v253
	v_mov_b32_e32 v130, v238
	v_mov_b32_e32 v131, v239
	v_mov_b32_e32 v128, v240
	v_mov_b32_e32 v129, v241
	v_mov_b32_e32 v126, v242
	v_mov_b32_e32 v127, v243
	v_mov_b32_e32 v124, v244
	v_mov_b32_e32 v125, v245
	v_mov_b32_e32 v122, v246
	v_mov_b32_e32 v123, v247
	v_mov_b32_e32 v118, v248
	v_mov_b32_e32 v119, v249
	v_mov_b32_e32 v116, v250
	v_mov_b32_e32 v117, v251
	v_mov_b32_e32 v112, v252
	v_mov_b32_e32 v113, v253
	v_mul_f32_e32 v28, v28, v109
	v_cvt_pk_bf16_f32 v28, v28, v83
	ds_write_b16 v174, v28
	v_mul_f32_e32 v28, v108, v189
	v_mul_f32_e32 v28, v29, v28
	v_cvt_pk_bf16_f32 v28, v28, v83
	ds_write_b16 v174, v28 offset:272
	v_mul_f32_e32 v28, v108, v198
	v_mul_f32_e32 v28, v30, v28
	v_cvt_pk_bf16_f32 v28, v28, v83
	ds_write_b16 v174, v28 offset:544
	v_mul_f32_e32 v28, v108, v199
	v_mul_f32_e32 v28, v31, v28
	v_cvt_pk_bf16_f32 v28, v28, v83
	ds_write_b16 v174, v28 offset:816
	v_mul_f32_e32 v28, v108, v200
	v_mul_f32_e32 v24, v24, v28
	v_cvt_pk_bf16_f32 v24, v24, v83
	ds_write_b16 v174, v24 offset:1088
	v_mul_f32_e32 v24, v108, v201
	v_mul_f32_e32 v24, v25, v24
	v_cvt_pk_bf16_f32 v24, v24, v83
	ds_write_b16 v174, v24 offset:1360
	v_mul_f32_e32 v24, v108, v202
	v_mul_f32_e32 v24, v26, v24
	v_cvt_pk_bf16_f32 v24, v24, v83
	ds_write_b16 v174, v24 offset:1632
	v_mul_f32_e32 v24, v108, v203
	v_mul_f32_e32 v24, v27, v24
	v_cvt_pk_bf16_f32 v24, v24, v83
	ds_write_b16 v174, v24 offset:1904
	v_mul_f32_e32 v24, v108, v204
	v_mul_f32_e32 v20, v20, v24
	v_cvt_pk_bf16_f32 v20, v20, v83
	ds_write_b16 v174, v20 offset:2176
	v_mul_f32_e32 v20, v108, v205
	v_mul_f32_e32 v20, v21, v20
	v_cvt_pk_bf16_f32 v20, v20, v83
	ds_write_b16 v174, v20 offset:2448
	v_mul_f32_e32 v20, v108, v206
	v_mul_f32_e32 v20, v22, v20
	v_cvt_pk_bf16_f32 v20, v20, v83
	ds_write_b16 v174, v20 offset:2720
	v_mul_f32_e32 v20, v108, v207
	v_mul_f32_e32 v20, v23, v20
	v_cvt_pk_bf16_f32 v20, v20, v83
	ds_write_b16 v174, v20 offset:2992
	v_mul_f32_e32 v20, v108, v208
	v_mul_f32_e32 v16, v16, v20
	v_cvt_pk_bf16_f32 v16, v16, v83
	ds_write_b16 v174, v16 offset:3264
	v_mul_f32_e32 v16, v108, v209
	v_mul_f32_e32 v16, v17, v16
	v_cvt_pk_bf16_f32 v16, v16, v83
	ds_write_b16 v174, v16 offset:3536
	v_mul_f32_e32 v16, v108, v210
	v_mul_f32_e32 v16, v18, v16
	v_cvt_pk_bf16_f32 v16, v16, v83
	ds_write_b16 v174, v16 offset:3808
	v_mul_f32_e32 v16, v108, v211
	v_mul_f32_e32 v16, v19, v16
	v_cvt_pk_bf16_f32 v16, v16, v83
	ds_write_b16 v174, v16 offset:4080
	v_mul_f32_e32 v16, v108, v212
	s_waitcnt vmcnt(4)
	v_mul_f32_e32 v16, v190, v16
	v_cvt_pk_bf16_f32 v16, v16, v83
	ds_write_b16 v174, v16 offset:4352
	v_mul_f32_e32 v16, v108, v213
	v_mul_f32_e32 v16, v191, v16
	v_mul_f32_e32 v4, v108, v4
	v_cvt_pk_bf16_f32 v16, v16, v83
	v_mul_f32_e32 v4, v165, v4
	ds_write_b16 v174, v16 offset:4624
	v_mul_f32_e32 v16, v108, v214
	v_cvt_pk_bf16_f32 v4, v4, v83
	v_mul_f32_e32 v16, v192, v16
	ds_write_b16 v174, v4 offset:6800
	v_mul_f32_e32 v4, v108, v161
	v_cvt_pk_bf16_f32 v16, v16, v83
	v_mul_f32_e32 v4, v166, v4
	ds_write_b16 v174, v16 offset:4896
	v_mul_f32_e32 v16, v108, v215
	v_cvt_pk_bf16_f32 v4, v4, v83
	v_mul_f32_e32 v16, v193, v16
	ds_write_b16 v174, v4 offset:7072
	v_mul_f32_e32 v4, v108, v160
	v_cvt_pk_bf16_f32 v16, v16, v83
	v_mul_f32_e32 v4, v167, v4
	ds_write_b16 v174, v16 offset:5168
	v_mul_f32_e32 v16, v108, v216
	v_cvt_pk_bf16_f32 v4, v4, v83
	v_mul_f32_e32 v16, v178, v16
	ds_write_b16 v174, v4 offset:7344
	v_mul_f32_e32 v4, v108, v195
	v_cvt_pk_bf16_f32 v16, v16, v83
	v_mul_f32_e32 v4, v40, v4
	ds_write_b16 v174, v16 offset:5440
	v_mul_f32_e32 v16, v108, v217
	v_cvt_pk_bf16_f32 v4, v4, v83
	v_mul_f32_e32 v16, v179, v16
	ds_write_b16 v174, v4 offset:7616
	v_mul_f32_e32 v4, v108, v194
	v_cvt_pk_bf16_f32 v16, v16, v83
	v_mul_f32_e32 v4, v41, v4
	ds_write_b16 v174, v16 offset:5712
	v_mul_f32_e32 v16, v108, v218
	v_cvt_pk_bf16_f32 v4, v4, v83
	v_mul_f32_e32 v16, v180, v16
	ds_write_b16 v174, v4 offset:7888
	v_mul_f32_e32 v4, v108, v197
	v_cvt_pk_bf16_f32 v16, v16, v83
	v_mul_f32_e32 v4, v42, v4
	ds_write_b16 v174, v16 offset:5984
	v_mul_f32_e32 v16, v108, v219
	v_cvt_pk_bf16_f32 v4, v4, v83
	v_mul_f32_e32 v16, v181, v16
	v_mul_f32_e32 v5, v108, v5
	ds_write_b16 v174, v4 offset:8160
	v_mul_f32_e32 v4, v108, v196
	v_cvt_pk_bf16_f32 v16, v16, v83
	v_mul_f32_e32 v5, v164, v5
	v_mul_f32_e32 v4, v43, v4
	ds_write_b16 v174, v16 offset:6256
	v_cvt_pk_bf16_f32 v5, v5, v83
	ds_write_b16 v174, v5 offset:6528
	v_cvt_pk_bf16_f32 v4, v4, v83
	ds_write_b16 v174, v4 offset:8432
	s_waitcnt lgkmcnt(0)
	s_barrier
; __device__ __forceinline__ float bf_lo(unsigned w) { return __uint_as_float(w << 16); }
; __device__ __forceinline__ float bf_hi(unsigned w) { return __uint_as_float(w & 0xffff0000u); }
; #define LAS __attribute__((address_space(3)))
; __device__ __forceinline__ unsigned cvt_pk_nv(float lo, float hi) { unsigned r; asm("v_cvt_pk_bf16_f32 %0, %1, %2" : "=v"(r) : "v"(lo), "v"(hi)); return r; }
; __device__ __forceinline__ void gmlp_tile(const Ctx& C, int T, LAS unsigned char* lds, int wave, int lane, int tid) {
;     ...
; #pragma unroll
;         for (int dbi = 0; dbi < 2; ++dbi) {
;             const int db = 2 * dh + dbi;
;             v16f acc;
; #pragma unroll
;             for (int r = 0; r < 16; ++r) acc[r] = 0.f;
; #pragma unroll
;             for (int ks = 0; ks < 8; ++ks) {
;                 const bfx8 va = *(const LAS bfx8*)(VT + (32 * db + tl) * VT_STRIDE + 16 * ks + 8 * hh);
;                 acc = __builtin_amdgcn_mfma_f32_32x32x16_bf16(va, wf[ks], acc, 0, 0, 0);
;             }
; #pragma unroll
;             for (int rg = 0; rg < 4; ++rg) {
;                 const v2u u2 = uw[dbi][rg];
;                 const float o0 = bf_lo(u2.x) * (acc[4 * rg + 0] + bias), o1 = bf_hi(u2.x) * (acc[4 * rg + 1] + bias);
;                 const float o2 = bf_lo(u2.y) * (acc[4 * rg + 2] + bias), o3 = bf_hi(u2.y) * (acc[4 * rg + 3] + bias);
;                 ssq += (o0 * o0 + o1 * o1) + (o2 * o2 + o3 * o3);
;                 outp[h][dbi][2 * rg] = cvt_pk_nv(o0, o1); outp[h][dbi][2 * rg + 1] = cvt_pk_nv(o2, o3);
;             }
	ds_read_b128 v[16:19], v102
	v_add_f32_e32 v4, v159, v7
	v_mul_f32_e32 v40, v4, v6
	v_mul_f32_e32 v4, v120, v120
	v_mul_f32_e32 v5, v40, v40
	v_fmac_f32_e32 v4, v158, v158
	v_fmac_f32_e32 v5, v220, v220
	v_add_f32_e32 v41, v4, v5
	ds_read_b128 v[4:7], v102 offset:32
	s_waitcnt lgkmcnt(1)
	v_mfma_f32_32x32x16_bf16 v[16:31], v[16:19], v[0:3], 0
	v_add_f32_e32 v108, v41, v157
	v_cvt_pk_bf16_f32 v157, v220, v40
	v_lshlrev_b32_e32 v40, 16, v114
	v_mul_f32_e32 v109, v8, v40
	ds_read_b128 v[40:43], v102 offset:64
	v_cvt_pk_bf16_f32 v160, v158, v120
	v_and_b32_e32 v8, 0xffff0000, v115
	s_waitcnt lgkmcnt(1)
	v_mfma_f32_32x32x16_bf16 v[16:31], v[4:7], v[76:79], v[16:31]
	v_and_b32_e32 v4, 0xffff0000, v114
	v_add_f32_e32 v5, v159, v9
	v_mul_f32_e32 v114, v5, v4
	v_lshlrev_b32_e32 v4, 16, v115
	v_add_f32_e32 v5, v159, v10
	v_mul_f32_e32 v120, v5, v4
	ds_read_b128 v[4:7], v102 offset:96
	s_waitcnt lgkmcnt(1)
	v_mfma_f32_32x32x16_bf16 v[16:31], v[40:43], v[72:75], v[16:31]
	v_add_f32_e32 v9, v159, v11
	v_mul_f32_e32 v40, v9, v8
	ds_read_b128 v[8:11], v102 offset:128
	v_mul_f32_e32 v41, v114, v114
	v_mul_f32_e32 v42, v40, v40
	v_fmac_f32_e32 v41, v109, v109
	v_fmac_f32_e32 v42, v120, v120
	s_waitcnt lgkmcnt(1)
	v_mfma_f32_32x32x16_bf16 v[16:31], v[4:7], v[68:71], v[16:31]
	v_add_f32_e32 v4, v41, v42
	v_add_f32_e32 v41, v4, v108
	ds_read_b128 v[4:7], v102 offset:160
	v_cvt_pk_bf16_f32 v158, v120, v40
	v_lshlrev_b32_e32 v40, 16, v110
	v_cvt_pk_bf16_f32 v161, v109, v114
	s_waitcnt vmcnt(3)
	v_and_b32_e32 v212, 0xffff0000, v36
	s_waitcnt lgkmcnt(1)
	v_mfma_f32_32x32x16_bf16 v[16:31], v[8:11], v[64:67], v[16:31]
	v_add_f32_e32 v8, v159, v12
	v_mul_f32_e32 v12, v8, v40
	v_and_b32_e32 v8, 0xffff0000, v110
	v_add_f32_e32 v9, v159, v13
	v_mul_f32_e32 v13, v9, v8
	ds_read_b128 v[8:11], v102 offset:192
	v_lshlrev_b32_e32 v40, 16, v111
	s_waitcnt lgkmcnt(1)
	v_mfma_f32_32x32x16_bf16 v[16:31], v[4:7], v[56:59], v[16:31]
	v_add_f32_e32 v4, v159, v14
	v_mul_f32_e32 v14, v4, v40
	v_and_b32_e32 v4, 0xffff0000, v111
	v_add_f32_e32 v5, v159, v15
	v_mul_f32_e32 v15, v5, v4
	ds_read_b128 v[4:7], v102 offset:224
	v_mul_f32_e32 v40, v13, v13
	s_waitcnt lgkmcnt(1)
	v_mfma_f32_32x32x16_bf16 v[16:31], v[8:11], v[48:51], v[16:31]
	v_mul_f32_e32 v8, v15, v15
	v_fmac_f32_e32 v40, v12, v12
	v_fmac_f32_e32 v8, v14, v14
	v_add_f32_e32 v8, v40, v8
	v_add_f32_e32 v8, v8, v41
	v_cvt_pk_bf16_f32 v162, v12, v13
	v_cvt_pk_bf16_f32 v159, v14, v15
	s_waitcnt lgkmcnt(0)
	v_mfma_f32_32x32x16_bf16 v[16:31], v[4:7], v[44:47], v[16:31]
	v_lshlrev_b32_e32 v4, 16, v130
	v_and_b32_e32 v208, 0xffff0000, v38
	v_lshlrev_b32_e32 v209, 16, v38
	v_lshlrev_b32_e32 v213, 16, v36
	v_mul_f32_e32 v38, v212, v212
	v_lshlrev_b32_e32 v211, 16, v37
	v_fmac_f32_e32 v38, v213, v213
	s_nop 4
	v_add_f32_e32 v5, v163, v16
	v_mul_f32_e32 v4, v5, v4
	v_and_b32_e32 v5, 0xffff0000, v130
	v_add_f32_e32 v6, v163, v17
	v_mul_f32_e32 v5, v6, v5
	v_lshlrev_b32_e32 v6, 16, v131
	v_add_f32_e32 v7, v163, v18
	v_mul_f32_e32 v6, v7, v6
	v_and_b32_e32 v7, 0xffff0000, v131
	v_add_f32_e32 v9, v163, v19
	v_mul_f32_e32 v7, v9, v7
	v_mul_f32_e32 v9, v5, v5
	v_fmac_f32_e32 v9, v4, v4
	v_cvt_pk_bf16_f32 v131, v4, v5
	v_lshlrev_b32_e32 v4, 16, v128
	v_add_f32_e32 v5, v163, v20
	v_mul_f32_e32 v20, v5, v4
	v_and_b32_e32 v4, 0xffff0000, v128
	v_add_f32_e32 v5, v163, v21
	v_mul_f32_e32 v10, v7, v7
	v_mul_f32_e32 v21, v5, v4
	v_lshlrev_b32_e32 v4, 16, v129
	v_add_f32_e32 v5, v163, v22
	v_fmac_f32_e32 v10, v6, v6
	v_cvt_pk_bf16_f32 v130, v6, v7
	v_mul_f32_e32 v22, v5, v4
	ds_read_b128 v[4:7], v102 offset:8704
	ds_read_b128 v[16:19], v102 offset:8736
	v_add_f32_e32 v9, v9, v10
	v_add_f32_e32 v40, v8, v9
	v_and_b32_e32 v8, 0xffff0000, v129
	v_add_f32_e32 v9, v163, v23
	v_mul_f32_e32 v23, v9, v8
	v_mul_f32_e32 v8, v21, v21
	v_mul_f32_e32 v9, v23, v23
	v_fmac_f32_e32 v8, v20, v20
	v_fmac_f32_e32 v9, v22, v22
	v_add_f32_e32 v41, v8, v9
	s_waitcnt lgkmcnt(1)
	v_mfma_f32_32x32x16_bf16 v[0:15], v[4:7], v[0:3], 0
	v_cvt_pk_bf16_f32 v129, v20, v21
	v_lshlrev_b32_e32 v20, 16, v126
	v_add_f32_e32 v21, v163, v24
	v_cvt_pk_bf16_f32 v128, v22, v23
	v_mul_f32_e32 v24, v21, v20
	ds_read_b128 v[20:23], v102 offset:8768
	v_add_f32_e32 v40, v41, v40
	s_waitcnt lgkmcnt(1)
	v_mfma_f32_32x32x16_bf16 v[0:15], v[16:19], v[76:79], v[0:15]
	v_and_b32_e32 v16, 0xffff0000, v126
	v_add_f32_e32 v17, v163, v25
	v_mul_f32_e32 v25, v17, v16
	v_lshlrev_b32_e32 v16, 16, v127
	v_add_f32_e32 v17, v163, v26
	v_mul_f32_e32 v26, v17, v16
	ds_read_b128 v[16:19], v102 offset:8800
	s_waitcnt lgkmcnt(1)
	v_mfma_f32_32x32x16_bf16 v[0:15], v[20:23], v[72:75], v[0:15]
	v_and_b32_e32 v20, 0xffff0000, v127
	v_add_f32_e32 v21, v163, v27
	v_mul_f32_e32 v27, v21, v20
	ds_read_b128 v[20:23], v102 offset:8832
	v_mul_f32_e32 v41, v25, v25
	v_mul_f32_e32 v42, v27, v27
	v_fmac_f32_e32 v41, v24, v24
	s_waitcnt lgkmcnt(1)
	v_mfma_f32_32x32x16_bf16 v[0:15], v[16:19], v[68:71], v[0:15]
	v_fmac_f32_e32 v42, v26, v26
	v_add_f32_e32 v16, v41, v42
	v_add_f32_e32 v40, v16, v40
	ds_read_b128 v[16:19], v102 offset:8864
	v_cvt_pk_bf16_f32 v127, v24, v25
	v_lshlrev_b32_e32 v24, 16, v124
	v_cvt_pk_bf16_f32 v126, v26, v27
	s_waitcnt lgkmcnt(1)
	v_mfma_f32_32x32x16_bf16 v[0:15], v[20:23], v[64:67], v[0:15]
	v_add_f32_e32 v20, v163, v28
	v_mul_f32_e32 v24, v20, v24
	v_and_b32_e32 v20, 0xffff0000, v124
	v_add_f32_e32 v21, v163, v29
	v_mul_f32_e32 v25, v21, v20
	ds_read_b128 v[20:23], v102 offset:8896
	v_lshlrev_b32_e32 v26, 16, v125
	s_waitcnt lgkmcnt(1)
	v_mfma_f32_32x32x16_bf16 v[0:15], v[16:19], v[56:59], v[0:15]
	v_add_f32_e32 v16, v163, v30
	v_mul_f32_e32 v26, v16, v26
	v_and_b32_e32 v16, 0xffff0000, v125
	v_add_f32_e32 v17, v163, v31
	v_mul_f32_e32 v27, v17, v16
	ds_read_b128 v[16:19], v102 offset:8928
	v_mul_f32_e32 v28, v25, v25
	s_waitcnt lgkmcnt(1)
; __device__ __forceinline__ float bf_lo(unsigned w) { return __uint_as_float(w << 16); }
; __device__ __forceinline__ float bf_hi(unsigned w) { return __uint_as_float(w & 0xffff0000u); }
;     __device__ __forceinline__ const float* in(int i) const { return karg_in(i); }
; __device__ __forceinline__ void gmlp_tile(const Ctx& C, int T, LAS unsigned char* lds, int wave, int lane, int tid) {
;     ...
;         const bf16* wrow = Weff + ((size_t)(mode * 4 + h) * 128 + t) * 128 + 8 * hh;
; #pragma unroll
;         for (int ks = 0; ks < 8; ++ks) wf[ks] = *(const bfx8*)(wrow + 16 * ks);
;         v2u uw[2][4];
; #pragma unroll
;         for (int dbi = 0; dbi < 2; ++dbi)
; #pragma unroll
;             for (int rg = 0; rg < 4; ++rg) uw[dbi][rg] = *(const v2u*)(zt + h * 128 + 32 * (2 * dh + dbi) + 8 * rg + 4 * hh);
;         const float bias = C.in(13)[h * 128 + (mode ? (t & 15) : t)];
;         v4f gvv[8];
;         { const float* gvp = C.in(11) + h * 128 + q * 32;
; #pragma unroll
;           for (int i = 0; i < 8; ++i) gvv[i] = *(const v4f*)(gvp + 4 * i); }
;         __syncthreads();
;         {
;             float v[32]; float s = 0.f;
; #pragma unroll
;             for (int i = 0; i < 4; ++i) { const v4u w = vraw[i];
;                 v[8 * i + 0] = bf_lo(w.x); v[8 * i + 1] = bf_hi(w.x); v[8 * i + 2] = bf_lo(w.y); v[8 * i + 3] = bf_hi(w.y);
;                 v[8 * i + 4] = bf_lo(w.z); v[8 * i + 5] = bf_hi(w.z); v[8 * i + 6] = bf_lo(w.w); v[8 * i + 7] = bf_hi(w.w); }
;             if (h < 3) {
; #pragma unroll
;                 for (int i = 0; i < 4; ++i) vraw[i] = *(const v4u*)(vsrc + (h + 1) * 128 + 8 * i);
;             }
; #pragma unroll
;             for (int i = 0; i < 32; ++i) s += v[i] * v[i];
	v_mfma_f32_32x32x16_bf16 v[0:15], v[20:23], v[48:51], v[0:15]
	v_mul_f32_e32 v20, v27, v27
	v_fmac_f32_e32 v28, v24, v24
	v_fmac_f32_e32 v20, v26, v26
	v_add_f32_e32 v20, v28, v20
	v_add_f32_e32 v20, v20, v40
	v_cvt_pk_bf16_f32 v125, v24, v25
	v_cvt_pk_bf16_f32 v124, v26, v27
	s_waitcnt lgkmcnt(0)
	v_mfma_f32_32x32x16_bf16 v[0:15], v[16:19], v[44:47], v[0:15]
	v_lshlrev_b32_e32 v16, 16, v122
	v_and_b32_e32 v210, 0xffff0000, v37
	v_fmac_f32_e32 v38, v211, v211
	v_fmac_f32_e32 v38, v210, v210
	v_fmac_f32_e32 v38, v209, v209
	v_lshlrev_b32_e32 v207, 16, v39
	v_fmac_f32_e32 v38, v208, v208
	s_nop 4
	v_add_f32_e32 v0, v163, v0
	v_mul_f32_e32 v18, v0, v16
	v_and_b32_e32 v0, 0xffff0000, v122
	v_add_f32_e32 v1, v163, v1
	v_mul_f32_e32 v19, v1, v0
	v_lshlrev_b32_e32 v0, 16, v123
	v_add_f32_e32 v1, v163, v2
	v_mul_f32_e32 v21, v1, v0
	v_and_b32_e32 v0, 0xffff0000, v123
	v_add_f32_e32 v1, v163, v3
	v_mul_f32_e32 v22, v1, v0
	v_mul_f32_e32 v0, v19, v19
	v_mul_f32_e32 v1, v22, v22
	v_add_co_u32_e32 v16, vcc, s41, v104
	v_fmac_f32_e32 v0, v18, v18
	v_fmac_f32_e32 v1, v21, v21
	v_addc_co_u32_e32 v17, vcc, 0, v105, vcc
	v_add_f32_e32 v23, v0, v1
	global_load_dwordx4 v[0:3], v[16:17], off offset:-3584
	global_load_dwordx4 v[72:75], v[16:17], off offset:-2560
	global_load_dwordx4 v[68:71], v[16:17], off offset:-1536
	global_load_dwordx4 v[64:67], v[16:17], off offset:-512
	global_load_dwordx4 v[56:59], v[16:17], off offset:512
	global_load_dwordx4 v[48:51], v[16:17], off offset:1536
	global_load_dwordx4 v[44:47], v[16:17], off offset:2560
	global_load_dwordx4 v[40:43], v[16:17], off offset:3584
	global_load_dwordx4 v[238:241], v[236:237], off offset:768
	global_load_dwordx4 v[242:245], v[236:237], off offset:800
	global_load_dwordx4 v[246:249], v[236:237], off offset:832
	global_load_dwordx4 v[250:253], v[236:237], off offset:864
	s_load_dwordx2 s[0:1], s[0:1], 0x68
	v_lshlrev_b32_e32 v16, 16, v118
	v_add_f32_e32 v4, v163, v4
	v_add_f32_e32 v180, v20, v23
	v_cvt_pk_bf16_f32 v107, v18, v19
	s_waitcnt lgkmcnt(0)
	global_load_dword v156, v156, s[0:1] offset:1536
	s_mov_b64 s[0:1], s[80:81]
	s_load_dwordx2 s[28:29], s[0:1], 0x58
	v_cvt_pk_bf16_f32 v106, v21, v22
	v_mul_f32_e32 v181, v4, v16
	s_waitcnt lgkmcnt(0)
	global_load_dwordx4 v[16:19], v139, s[28:29] offset:1584
	global_load_dwordx4 v[20:23], v139, s[28:29] offset:1568
	global_load_dwordx4 v[24:27], v139, s[28:29] offset:1552
	global_load_dwordx4 v[28:31], v139, s[28:29] offset:1536
	v_and_b32_e32 v206, 0xffff0000, v39
	v_fmac_f32_e32 v38, v207, v207
	s_waitcnt vmcnt(19)
	v_lshlrev_b32_e32 v205, 16, v52
	v_fmac_f32_e32 v38, v206, v206
	v_and_b32_e32 v204, 0xffff0000, v52
	v_fmac_f32_e32 v38, v205, v205
	v_lshlrev_b32_e32 v203, 16, v53
	v_fmac_f32_e32 v38, v204, v204
	v_and_b32_e32 v202, 0xffff0000, v53
	v_fmac_f32_e32 v38, v203, v203
	v_lshlrev_b32_e32 v201, 16, v54
	v_fmac_f32_e32 v38, v202, v202
	v_and_b32_e32 v200, 0xffff0000, v54
	v_fmac_f32_e32 v38, v201, v201
	v_lshlrev_b32_e32 v199, 16, v55
	v_fmac_f32_e32 v38, v200, v200
	v_and_b32_e32 v198, 0xffff0000, v55
	v_fmac_f32_e32 v38, v199, v199
	s_waitcnt vmcnt(17)
	v_lshlrev_b32_e32 v197, 16, v60
	v_fmac_f32_e32 v38, v198, v198
	v_and_b32_e32 v196, 0xffff0000, v60
	v_fmac_f32_e32 v38, v197, v197
	v_lshlrev_b32_e32 v195, 16, v61
	v_fmac_f32_e32 v38, v196, v196
	v_and_b32_e32 v194, 0xffff0000, v61
	v_fmac_f32_e32 v38, v195, v195
	v_lshlrev_b32_e32 v193, 16, v62
	v_fmac_f32_e32 v38, v194, v194
	v_and_b32_e32 v192, 0xffff0000, v62
	v_fmac_f32_e32 v38, v193, v193
	v_lshlrev_b32_e32 v191, 16, v63
	v_fmac_f32_e32 v38, v192, v192
	v_add_f32_e32 v189, v163, v5
	v_and_b32_e32 v190, 0xffff0000, v63
	v_fmac_f32_e32 v38, v191, v191
	v_and_b32_e32 v4, 0xffff0000, v32
	v_lshlrev_b32_e32 v5, 16, v32
	v_fmac_f32_e32 v38, v190, v190
	v_pk_mul_f32 v[36:37], v[4:5], v[4:5]
	v_and_b32_e32 v164, 0xffff0000, v33
	v_add_f32_e32 v32, v37, v38
	v_lshlrev_b32_e32 v165, 16, v33
	v_add_f32_e32 v36, v36, v32
	v_pk_mul_f32 v[32:33], v[164:165], v[164:165]
	v_and_b32_e32 v166, 0xffff0000, v34
	v_add_f32_e32 v33, v33, v36
	v_lshlrev_b32_e32 v167, 16, v34
	v_add_f32_e32 v36, v32, v33
	v_pk_mul_f32 v[32:33], v[166:167], v[166:167]
	v_and_b32_e32 v178, 0xffff0000, v35
	v_add_f32_e32 v33, v33, v36
	v_lshlrev_b32_e32 v179, 16, v35
	v_add_f32_e32 v34, v32, v33
	v_pk_mul_f32 v[32:33], v[178:179], v[178:179]
	v_and_b32_e32 v118, 0xffff0000, v118
	v_add_f32_e32 v33, v33, v34
	v_add_f32_e32 v32, v32, v33
	ds_bpermute_b32 v33, v183, v32
	v_lshlrev_b32_e32 v34, 16, v119
	v_add_f32_e32 v6, v163, v6
	v_mul_f32_e32 v118, v189, v118
	v_mul_f32_e32 v189, v6, v34
	s_waitcnt lgkmcnt(0)
	v_add_f32_e32 v6, v32, v33
	global_load_dwordx4 v[32:35], v139, s[28:29] offset:1616
	global_load_dwordx4 v[36:39], v139, s[28:29] offset:1600
	global_load_dwordx4 v[52:55], v139, s[28:29] offset:1648
	global_load_dwordx4 v[60:63], v139, s[28:29] offset:1632
	ds_bpermute_b32 v214, v184, v6
	s_waitcnt lgkmcnt(0)
	s_barrier
; __device__ __forceinline__ float bf_lo(unsigned w) { return __uint_as_float(w << 16); }
; __device__ __forceinline__ float bf_hi(unsigned w) { return __uint_as_float(w & 0xffff0000u); }
; __device__ __forceinline__ bf16 f2bf(float f) { return (bf16)(cvt_pk_nv(f, 0.f) & 0xffffu); }
; __device__ __forceinline__ void gmlp_tile(const Ctx& C, int T, LAS unsigned char* lds, int wave, int lane, int tid) {
;     ...
;         __syncthreads();
;         {
;             float v[32]; float s = 0.f;
; #pragma unroll
;             for (int i = 0; i < 4; ++i) { const v4u w = vraw[i];
;                 v[8 * i + 0] = bf_lo(w.x); v[8 * i + 1] = bf_hi(w.x); v[8 * i + 2] = bf_lo(w.y); v[8 * i + 3] = bf_hi(w.y);
;                 v[8 * i + 4] = bf_lo(w.z); v[8 * i + 5] = bf_hi(w.z); v[8 * i + 6] = bf_lo(w.w); v[8 * i + 7] = bf_hi(w.w); }
;             if (h < 3) {
; #pragma unroll
;                 for (int i = 0; i < 4; ++i) vraw[i] = *(const v4u*)(vsrc + (h + 1) * 128 + 8 * i);
;             }
; #pragma unroll
;             for (int i = 0; i < 32; ++i) s += v[i] * v[i];
;             s += __shfl_xor(s, 1); s += __shfl_xor(s, 2);
;             const float r = rsqrtf(s * (1.f / 128.f) + EPS);
; #pragma unroll
;             for (int i = 0; i < 32; ++i) { v[i] = v[i] * r * gvv[i >> 2][i & 3]; VT[(q * 32 + i) * VT_STRIDE + row] = f2bf(v[i]); }
	v_and_b32_e32 v119, 0xffff0000, v119
	v_add_f32_e32 v6, v6, v214
	v_fmamk_f32 v6, v6, 0x3c000000, v177
	v_mul_f32_e32 v139, 0x4b800000, v6
	v_cmp_gt_f32_e32 vcc, s38, v6
	v_add_f32_e32 v8, v163, v8
	s_nop 0
	v_cndmask_b32_e32 v6, v6, v139, vcc
	v_rsq_f32_e32 v6, v6
	s_nop 0
	v_mul_f32_e32 v139, 0x45800000, v6
	v_cndmask_b32_e32 v6, v6, v139, vcc
	v_mul_f32_e32 v139, v6, v213
	s_waitcnt vmcnt(4)
	v_permlane32_swap_b32_e32 v238, v240
	v_permlane32_swap_b32_e32 v239, v241
	v_permlane32_swap_b32_e32 v242, v244
	v_permlane32_swap_b32_e32 v243, v245
	v_permlane32_swap_b32_e32 v246, v248
	v_permlane32_swap_b32_e32 v247, v249
	v_permlane32_swap_b32_e32 v250, v252
	v_permlane32_swap_b32_e32 v251, v253
	v_mov_b32_e32 v122, v238
	v_mov_b32_e32 v123, v239
	v_mov_b32_e32 v120, v240
	v_mov_b32_e32 v121, v241
	v_mov_b32_e32 v114, v242
	v_mov_b32_e32 v115, v243
	v_mov_b32_e32 v110, v244
	v_mov_b32_e32 v111, v245
	v_mov_b32_e32 v108, v246
	v_mov_b32_e32 v109, v247
	v_mov_b32_e32 v104, v248
	v_mov_b32_e32 v105, v249
	v_mov_b32_e32 v78, v250
	v_mov_b32_e32 v79, v251
	v_mov_b32_e32 v76, v252
	v_mov_b32_e32 v77, v253
	v_mul_f32_e32 v28, v28, v139
	v_cvt_pk_bf16_f32 v28, v28, v83
	ds_write_b16 v174, v28
	v_mul_f32_e32 v28, v6, v212
	v_mul_f32_e32 v28, v29, v28
	v_cvt_pk_bf16_f32 v28, v28, v83
	ds_write_b16 v174, v28 offset:272
	v_mul_f32_e32 v28, v6, v211
	v_mul_f32_e32 v28, v30, v28
	v_cvt_pk_bf16_f32 v28, v28, v83
	ds_write_b16 v174, v28 offset:544
	v_mul_f32_e32 v28, v6, v210
	v_mul_f32_e32 v28, v31, v28
	v_cvt_pk_bf16_f32 v28, v28, v83
	ds_write_b16 v174, v28 offset:816
	v_mul_f32_e32 v28, v6, v209
	v_mul_f32_e32 v24, v24, v28
	v_cvt_pk_bf16_f32 v24, v24, v83
	ds_write_b16 v174, v24 offset:1088
	v_mul_f32_e32 v24, v6, v208
	v_mul_f32_e32 v24, v25, v24
	v_cvt_pk_bf16_f32 v24, v24, v83
	ds_write_b16 v174, v24 offset:1360
	v_mul_f32_e32 v24, v6, v207
	v_mul_f32_e32 v24, v26, v24
	v_cvt_pk_bf16_f32 v24, v24, v83
	ds_write_b16 v174, v24 offset:1632
	v_mul_f32_e32 v24, v6, v206
	v_mul_f32_e32 v24, v27, v24
	v_cvt_pk_bf16_f32 v24, v24, v83
	ds_write_b16 v174, v24 offset:1904
	v_mul_f32_e32 v24, v6, v205
	v_mul_f32_e32 v20, v20, v24
	v_cvt_pk_bf16_f32 v20, v20, v83
	ds_write_b16 v174, v20 offset:2176
	v_mul_f32_e32 v20, v6, v204
	v_mul_f32_e32 v20, v21, v20
	v_cvt_pk_bf16_f32 v20, v20, v83
	ds_write_b16 v174, v20 offset:2448
	v_mul_f32_e32 v20, v6, v203
	v_mul_f32_e32 v20, v22, v20
	v_cvt_pk_bf16_f32 v20, v20, v83
	ds_write_b16 v174, v20 offset:2720
	v_mul_f32_e32 v20, v6, v202
	v_mul_f32_e32 v20, v23, v20
	v_cvt_pk_bf16_f32 v20, v20, v83
	ds_write_b16 v174, v20 offset:2992
	v_mul_f32_e32 v20, v6, v201
	v_mul_f32_e32 v16, v16, v20
	v_cvt_pk_bf16_f32 v16, v16, v83
	ds_write_b16 v174, v16 offset:3264
	v_mul_f32_e32 v16, v6, v200
	v_mul_f32_e32 v16, v17, v16
	v_cvt_pk_bf16_f32 v16, v16, v83
	ds_write_b16 v174, v16 offset:3536
	v_mul_f32_e32 v16, v6, v199
	v_mul_f32_e32 v16, v18, v16
	v_cvt_pk_bf16_f32 v16, v16, v83
	ds_write_b16 v174, v16 offset:3808
	v_mul_f32_e32 v16, v6, v198
	v_mul_f32_e32 v16, v19, v16
	v_cvt_pk_bf16_f32 v16, v16, v83
	ds_write_b16 v174, v16 offset:4080
	v_mul_f32_e32 v16, v6, v197
	s_waitcnt vmcnt(2)
	v_mul_f32_e32 v16, v36, v16
	v_cvt_pk_bf16_f32 v16, v16, v83
	ds_write_b16 v174, v16 offset:4352
	v_mul_f32_e32 v16, v6, v196
	v_mul_f32_e32 v16, v37, v16
	v_mul_f32_e32 v4, v6, v4
	v_cvt_pk_bf16_f32 v16, v16, v83
	s_waitcnt vmcnt(0)
	v_mul_f32_e32 v4, v61, v4
	ds_write_b16 v174, v16 offset:4624
	v_mul_f32_e32 v16, v6, v195
	v_cvt_pk_bf16_f32 v4, v4, v83
	v_mul_f32_e32 v16, v38, v16
	ds_write_b16 v174, v4 offset:6800
	v_mul_f32_e32 v4, v6, v165
	v_cvt_pk_bf16_f32 v16, v16, v83
	v_mul_f32_e32 v4, v62, v4
	ds_write_b16 v174, v16 offset:4896
	v_mul_f32_e32 v16, v6, v194
	v_cvt_pk_bf16_f32 v4, v4, v83
	v_mul_f32_e32 v16, v39, v16
	ds_write_b16 v174, v4 offset:7072
	v_mul_f32_e32 v4, v6, v164
	v_cvt_pk_bf16_f32 v16, v16, v83
	v_mul_f32_e32 v4, v63, v4
	ds_write_b16 v174, v16 offset:5168
	v_mul_f32_e32 v16, v6, v193
	v_cvt_pk_bf16_f32 v4, v4, v83
	v_mul_f32_e32 v16, v32, v16
	ds_write_b16 v174, v4 offset:7344
	v_mul_f32_e32 v4, v6, v167
	v_cvt_pk_bf16_f32 v16, v16, v83
	v_mul_f32_e32 v4, v52, v4
	ds_write_b16 v174, v16 offset:5440
	v_mul_f32_e32 v16, v6, v192
	v_cvt_pk_bf16_f32 v4, v4, v83
	v_mul_f32_e32 v16, v33, v16
	ds_write_b16 v174, v4 offset:7616
	v_mul_f32_e32 v4, v6, v166
	v_cvt_pk_bf16_f32 v16, v16, v83
	v_mul_f32_e32 v4, v53, v4
	ds_write_b16 v174, v16 offset:5712
	v_mul_f32_e32 v16, v6, v191
	v_cvt_pk_bf16_f32 v4, v4, v83
	v_mul_f32_e32 v16, v34, v16
	ds_write_b16 v174, v4 offset:7888
	v_mul_f32_e32 v4, v6, v179
	v_cvt_pk_bf16_f32 v16, v16, v83
	v_mul_f32_e32 v4, v54, v4
	ds_write_b16 v174, v16 offset:5984
	v_mul_f32_e32 v16, v6, v190
	v_cvt_pk_bf16_f32 v4, v4, v83
	v_mul_f32_e32 v16, v35, v16
	v_mul_f32_e32 v5, v6, v5
	ds_write_b16 v174, v4 offset:8160
	v_mul_f32_e32 v4, v6, v178
	v_cvt_pk_bf16_f32 v16, v16, v83
	v_mul_f32_e32 v5, v60, v5
	v_mul_f32_e32 v4, v55, v4
	ds_write_b16 v174, v16 offset:6256
	v_cvt_pk_bf16_f32 v5, v5, v83
	ds_write_b16 v174, v5 offset:6528
	v_cvt_pk_bf16_f32 v4, v4, v83
	ds_write_b16 v174, v4 offset:8432
	s_waitcnt lgkmcnt(0)
	s_barrier
; __device__ __forceinline__ float bf_lo(unsigned w) { return __uint_as_float(w << 16); }
; __device__ __forceinline__ float bf_hi(unsigned w) { return __uint_as_float(w & 0xffff0000u); }
; #define LAS __attribute__((address_space(3)))
; __device__ __forceinline__ unsigned cvt_pk_nv(float lo, float hi) { unsigned r; asm("v_cvt_pk_bf16_f32 %0, %1, %2" : "=v"(r) : "v"(lo), "v"(hi)); return r; }
; __device__ __forceinline__ void gmlp_tile(const Ctx& C, int T, LAS unsigned char* lds, int wave, int lane, int tid) {
;     ...
; #pragma unroll
;         for (int dbi = 0; dbi < 2; ++dbi) {
;             const int db = 2 * dh + dbi;
;             v16f acc;
; #pragma unroll
;             for (int r = 0; r < 16; ++r) acc[r] = 0.f;
; #pragma unroll
;             for (int ks = 0; ks < 8; ++ks) {
;                 const bfx8 va = *(const LAS bfx8*)(VT + (32 * db + tl) * VT_STRIDE + 16 * ks + 8 * hh);
;                 acc = __builtin_amdgcn_mfma_f32_32x32x16_bf16(va, wf[ks], acc, 0, 0, 0);
;             }
; #pragma unroll
;             for (int rg = 0; rg < 4; ++rg) {
;                 const v2u u2 = uw[dbi][rg];
;                 const float o0 = bf_lo(u2.x) * (acc[4 * rg + 0] + bias), o1 = bf_hi(u2.x) * (acc[4 * rg + 1] + bias);
;                 const float o2 = bf_lo(u2.y) * (acc[4 * rg + 2] + bias), o3 = bf_hi(u2.y) * (acc[4 * rg + 3] + bias);
;                 ssq += (o0 * o0 + o1 * o1) + (o2 * o2 + o3 * o3);
;                 outp[h][dbi][2 * rg] = cvt_pk_nv(o0, o1); outp[h][dbi][2 * rg + 1] = cvt_pk_nv(o2, o3);
;             }
	ds_read_b128 v[16:19], v102
	v_add_f32_e32 v4, v163, v7
	v_mul_f32_e32 v32, v4, v119
	v_mul_f32_e32 v4, v118, v118
	v_mul_f32_e32 v5, v32, v32
	v_fmac_f32_e32 v4, v181, v181
	v_fmac_f32_e32 v5, v189, v189
	v_add_f32_e32 v33, v4, v5
	ds_read_b128 v[4:7], v102 offset:32
	s_waitcnt lgkmcnt(1)
	v_mfma_f32_32x32x16_bf16 v[16:31], v[16:19], v[0:3], 0
	ds_read_b128 v[36:39], v102 offset:64
	v_lshlrev_b32_e32 v34, 16, v116
	v_mul_f32_e32 v34, v8, v34
	v_and_b32_e32 v8, 0xffff0000, v117
	v_add_f32_e32 v33, v33, v180
	ds_read_b128 v[60:63], v102 offset:8768
	v_cvt_pk_bf16_f32 v35, v181, v118
	s_waitcnt lgkmcnt(2)
	v_mfma_f32_32x32x16_bf16 v[16:31], v[4:7], v[72:75], v[16:31]
	v_and_b32_e32 v4, 0xffff0000, v116
	v_add_f32_e32 v5, v163, v9
	v_mul_f32_e32 v52, v5, v4
	v_lshlrev_b32_e32 v4, 16, v117
	v_add_f32_e32 v5, v163, v10
	v_mul_f32_e32 v53, v5, v4
	ds_read_b128 v[4:7], v102 offset:96
	s_waitcnt lgkmcnt(2)
	v_mfma_f32_32x32x16_bf16 v[16:31], v[36:39], v[68:71], v[16:31]
	v_add_f32_e32 v9, v163, v11
	v_mul_f32_e32 v37, v9, v8
	ds_read_b128 v[8:11], v102 offset:128
	v_mul_f32_e32 v36, v52, v52
	v_mul_f32_e32 v38, v37, v37
	v_fmac_f32_e32 v36, v34, v34
	v_fmac_f32_e32 v38, v53, v53
	s_waitcnt lgkmcnt(1)
	v_mfma_f32_32x32x16_bf16 v[16:31], v[4:7], v[64:67], v[16:31]
	v_add_f32_e32 v4, v36, v38
	v_add_f32_e32 v38, v4, v33
	ds_read_b128 v[4:7], v102 offset:160
	v_cvt_pk_bf16_f32 v36, v34, v52
	v_lshlrev_b32_e32 v34, 16, v112
	v_cvt_pk_bf16_f32 v33, v53, v37
	ds_read_b128 v[52:55], v102 offset:8736
	s_waitcnt lgkmcnt(2)
	v_mfma_f32_32x32x16_bf16 v[16:31], v[8:11], v[56:59], v[16:31]
	v_add_f32_e32 v8, v163, v12
	v_mul_f32_e32 v12, v8, v34
	v_and_b32_e32 v8, 0xffff0000, v112
	v_add_f32_e32 v9, v163, v13
	v_mul_f32_e32 v13, v9, v8
	ds_read_b128 v[8:11], v102 offset:192
	v_lshlrev_b32_e32 v34, 16, v113
	s_waitcnt lgkmcnt(2)
	v_mfma_f32_32x32x16_bf16 v[16:31], v[4:7], v[48:51], v[16:31]
	v_add_f32_e32 v4, v163, v14
	v_mul_f32_e32 v14, v4, v34
	v_and_b32_e32 v4, 0xffff0000, v113
	v_add_f32_e32 v5, v163, v15
	v_mul_f32_e32 v15, v5, v4
	ds_read_b128 v[4:7], v102 offset:224
	v_mul_f32_e32 v34, v13, v13
	s_waitcnt lgkmcnt(1)
	v_mfma_f32_32x32x16_bf16 v[16:31], v[8:11], v[44:47], v[16:31]
	v_mul_f32_e32 v8, v15, v15
	v_fmac_f32_e32 v34, v12, v12
	v_fmac_f32_e32 v8, v14, v14
	v_add_f32_e32 v8, v34, v8
	v_add_f32_e32 v8, v8, v38
	v_cvt_pk_bf16_f32 v37, v12, v13
	v_cvt_pk_bf16_f32 v34, v14, v15
	s_waitcnt lgkmcnt(0)
	v_mfma_f32_32x32x16_bf16 v[16:31], v[4:7], v[40:43], v[16:31]
	v_lshlrev_b32_e32 v4, 16, v122
	v_and_b32_e32 v39, 0xffff0000, v115
	v_cvt_pk_bf16_f32 v32, v189, v32
	s_nop 9
	v_add_f32_e32 v5, v156, v16
	v_mul_f32_e32 v4, v5, v4
	v_and_b32_e32 v5, 0xffff0000, v122
	v_add_f32_e32 v6, v156, v17
	v_mul_f32_e32 v5, v6, v5
	v_lshlrev_b32_e32 v6, 16, v123
	v_add_f32_e32 v7, v156, v18
	v_mul_f32_e32 v6, v7, v6
	v_and_b32_e32 v7, 0xffff0000, v123
	v_add_f32_e32 v9, v156, v19
	v_mul_f32_e32 v7, v9, v7
	v_mul_f32_e32 v9, v5, v5
	v_fmac_f32_e32 v9, v4, v4
	v_cvt_pk_bf16_f32 v17, v4, v5
	v_lshlrev_b32_e32 v4, 16, v120
	v_add_f32_e32 v5, v156, v20
	v_mul_f32_e32 v19, v5, v4
	v_and_b32_e32 v4, 0xffff0000, v120
	v_add_f32_e32 v5, v156, v21
	v_mul_f32_e32 v10, v7, v7
	v_mul_f32_e32 v20, v5, v4
	v_lshlrev_b32_e32 v4, 16, v121
	v_add_f32_e32 v5, v156, v22
	v_fmac_f32_e32 v10, v6, v6
	v_cvt_pk_bf16_f32 v16, v6, v7
	v_mul_f32_e32 v21, v5, v4
	ds_read_b128 v[4:7], v102 offset:8704
	v_add_f32_e32 v9, v9, v10
	v_add_f32_e32 v18, v8, v9
	v_and_b32_e32 v8, 0xffff0000, v121
	v_add_f32_e32 v9, v156, v23
	v_mul_f32_e32 v22, v9, v8
	v_mul_f32_e32 v8, v20, v20
	v_mul_f32_e32 v9, v22, v22
	v_fmac_f32_e32 v8, v19, v19
	v_fmac_f32_e32 v9, v21, v21
	v_add_f32_e32 v23, v8, v9
	s_waitcnt lgkmcnt(0)
	v_mfma_f32_32x32x16_bf16 v[0:15], v[4:7], v[0:3], 0
	v_add_f32_e32 v38, v23, v18
	v_cvt_pk_bf16_f32 v20, v19, v20
	v_cvt_pk_bf16_f32 v18, v21, v22
	v_lshlrev_b32_e32 v19, 16, v114
	v_add_f32_e32 v21, v156, v24
	v_mul_f32_e32 v19, v21, v19
	v_and_b32_e32 v21, 0xffff0000, v114
	v_mfma_f32_32x32x16_bf16 v[0:15], v[52:55], v[72:75], v[0:15]
	v_add_f32_e32 v22, v156, v25
	v_mul_f32_e32 v21, v22, v21
	v_lshlrev_b32_e32 v22, 16, v115
	v_add_f32_e32 v23, v156, v26
	v_mul_f32_e32 v26, v23, v22
	ds_read_b128 v[22:25], v102 offset:8800
	ds_read_b128 v[52:55], v102 offset:8832
	v_mfma_f32_32x32x16_bf16 v[0:15], v[60:63], v[68:71], v[0:15]
	v_add_f32_e32 v27, v156, v27
	v_mul_f32_e32 v27, v27, v39
	v_mul_f32_e32 v39, v21, v21
	v_mul_f32_e32 v60, v27, v27
	v_fmac_f32_e32 v39, v19, v19
	v_fmac_f32_e32 v60, v26, v26
	v_cvt_pk_bf16_f32 v21, v19, v21
	s_waitcnt lgkmcnt(1)
; __device__ __forceinline__ float bf_lo(unsigned w) { return __uint_as_float(w << 16); }
; __device__ __forceinline__ float bf_hi(unsigned w) { return __uint_as_float(w & 0xffff0000u); }
; #define LAS __attribute__((address_space(3)))
; __device__ __forceinline__ unsigned cvt_pk_nv(float lo, float hi) { unsigned r; asm("v_cvt_pk_bf16_f32 %0, %1, %2" : "=v"(r) : "v"(lo), "v"(hi)); return r; }
; __device__ __forceinline__ void gmlp_tile(const Ctx& C, int T, LAS unsigned char* lds, int wave, int lane, int tid) {
;     ...
; #pragma unroll
;         for (int dbi = 0; dbi < 2; ++dbi) {
;             const int db = 2 * dh + dbi;
;             v16f acc;
; #pragma unroll
;             for (int r = 0; r < 16; ++r) acc[r] = 0.f;
; #pragma unroll
;             for (int ks = 0; ks < 8; ++ks) {
;                 const bfx8 va = *(const LAS bfx8*)(VT + (32 * db + tl) * VT_STRIDE + 16 * ks + 8 * hh);
;                 acc = __builtin_amdgcn_mfma_f32_32x32x16_bf16(va, wf[ks], acc, 0, 0, 0);
;             }
; #pragma unroll
;             for (int rg = 0; rg < 4; ++rg) {
;                 const v2u u2 = uw[dbi][rg];
;                 const float o0 = bf_lo(u2.x) * (acc[4 * rg + 0] + bias), o1 = bf_hi(u2.x) * (acc[4 * rg + 1] + bias);
;                 const float o2 = bf_lo(u2.y) * (acc[4 * rg + 2] + bias), o3 = bf_hi(u2.y) * (acc[4 * rg + 3] + bias);
;                 ssq += (o0 * o0 + o1 * o1) + (o2 * o2 + o3 * o3);
;                 outp[h][dbi][2 * rg] = cvt_pk_nv(o0, o1); outp[h][dbi][2 * rg + 1] = cvt_pk_nv(o2, o3);
;             }
;         }
;     }
;     ssq += __shfl_xor(ssq, 32);
;     if (hh == 0) SSQ[t * 2 + dh] = ssq;
	v_mfma_f32_32x32x16_bf16 v[0:15], v[22:25], v[64:67], v[0:15]
	v_add_f32_e32 v22, v39, v60
	v_add_f32_e32 v38, v22, v38
	ds_read_b128 v[22:25], v102 offset:8864
	v_cvt_pk_bf16_f32 v19, v26, v27
	v_lshlrev_b32_e32 v26, 16, v110
	v_add_f32_e32 v27, v156, v28
	v_mul_f32_e32 v39, v27, v26
	s_waitcnt lgkmcnt(1)
	v_mfma_f32_32x32x16_bf16 v[0:15], v[52:55], v[56:59], v[0:15]
	v_and_b32_e32 v26, 0xffff0000, v110
	v_add_f32_e32 v27, v156, v29
	v_mul_f32_e32 v52, v27, v26
	ds_read_b128 v[26:29], v102 offset:8896
	v_lshlrev_b32_e32 v53, 16, v111
	s_waitcnt lgkmcnt(1)
	v_mfma_f32_32x32x16_bf16 v[0:15], v[22:25], v[48:51], v[0:15]
	ds_read_b128 v[48:51], v102 offset:8928
	v_and_b32_e32 v23, 0xffff0000, v111
	v_add_f32_e32 v24, v156, v31
	v_add_f32_e32 v22, v156, v30
	v_mul_f32_e32 v24, v24, v23
	v_mul_f32_e32 v22, v22, v53
	v_mul_f32_e32 v25, v24, v24
	s_waitcnt lgkmcnt(1)
	v_mfma_f32_32x32x16_bf16 v[0:15], v[26:29], v[44:47], v[0:15]
	v_fmac_f32_e32 v25, v22, v22
	v_cvt_pk_bf16_f32 v22, v22, v24
	v_lshlrev_b32_e32 v24, 16, v108
	v_mul_f32_e32 v23, v52, v52
	v_fmac_f32_e32 v23, v39, v39
	v_add_f32_e32 v23, v23, v25
	v_add_f32_e32 v25, v23, v38
	s_waitcnt lgkmcnt(0)
	v_mfma_f32_32x32x16_bf16 v[0:15], v[48:51], v[40:43], v[0:15]
	v_cvt_pk_bf16_f32 v23, v39, v52
	s_nop 11
	v_add_f32_e32 v0, v156, v0
	v_mul_f32_e32 v0, v0, v24
	v_and_b32_e32 v24, 0xffff0000, v108
	v_add_f32_e32 v1, v156, v1
	v_mul_f32_e32 v1, v1, v24
	v_lshlrev_b32_e32 v24, 16, v109
	v_add_f32_e32 v2, v156, v2
	v_mul_f32_e32 v2, v2, v24
	v_and_b32_e32 v24, 0xffff0000, v109
	v_add_f32_e32 v3, v156, v3
	v_mul_f32_e32 v24, v3, v24
	v_mul_f32_e32 v3, v1, v1
	v_mul_f32_e32 v26, v24, v24
	v_fmac_f32_e32 v3, v0, v0
	v_fmac_f32_e32 v26, v2, v2
	v_add_f32_e32 v3, v3, v26
	v_add_f32_e32 v25, v25, v3
	v_cvt_pk_bf16_f32 v3, v0, v1
	v_lshlrev_b32_e32 v0, 16, v104
	v_add_f32_e32 v1, v156, v4
	v_mul_f32_e32 v0, v1, v0
	v_and_b32_e32 v1, 0xffff0000, v104
	v_add_f32_e32 v4, v156, v5
	v_mul_f32_e32 v1, v4, v1
	v_lshlrev_b32_e32 v4, 16, v105
	v_add_f32_e32 v5, v156, v6
	v_mul_f32_e32 v4, v5, v4
	v_and_b32_e32 v5, 0xffff0000, v105
	v_add_f32_e32 v6, v156, v7
	v_mul_f32_e32 v6, v6, v5
	v_mul_f32_e32 v5, v1, v1
	v_mul_f32_e32 v7, v6, v6
	v_fmac_f32_e32 v5, v0, v0
	v_fmac_f32_e32 v7, v4, v4
	v_add_f32_e32 v5, v5, v7
	v_add_f32_e32 v7, v5, v25
	v_cvt_pk_bf16_f32 v5, v0, v1
	v_lshlrev_b32_e32 v0, 16, v78
	v_add_f32_e32 v1, v156, v8
	v_cvt_pk_bf16_f32 v4, v4, v6
	v_mul_f32_e32 v0, v1, v0
	v_and_b32_e32 v1, 0xffff0000, v78
	v_add_f32_e32 v6, v156, v9
	v_mul_f32_e32 v1, v6, v1
	v_lshlrev_b32_e32 v6, 16, v79
	v_add_f32_e32 v8, v156, v10
	v_mul_f32_e32 v8, v8, v6
	v_and_b32_e32 v6, 0xffff0000, v79
	v_add_f32_e32 v9, v156, v11
	v_mul_f32_e32 v9, v9, v6
	v_mul_f32_e32 v6, v1, v1
	v_mul_f32_e32 v10, v9, v9
	v_fmac_f32_e32 v6, v0, v0
	v_fmac_f32_e32 v10, v8, v8
	v_add_f32_e32 v6, v6, v10
	v_add_f32_e32 v7, v6, v7
	v_cvt_pk_bf16_f32 v6, v0, v1
	v_lshlrev_b32_e32 v0, 16, v76
	v_add_f32_e32 v1, v156, v12
	v_mul_f32_e32 v0, v1, v0
	v_and_b32_e32 v1, 0xffff0000, v76
	v_add_f32_e32 v10, v156, v13
	v_mul_f32_e32 v11, v10, v1
	v_lshlrev_b32_e32 v1, 16, v77
	v_add_f32_e32 v10, v156, v14
	v_mul_f32_e32 v12, v10, v1
	v_and_b32_e32 v1, 0xffff0000, v77
	v_add_f32_e32 v10, v156, v15
	v_mul_f32_e32 v13, v10, v1
	v_mul_f32_e32 v1, v11, v11
	v_mul_f32_e32 v10, v13, v13
	v_fmac_f32_e32 v1, v0, v0
	v_fmac_f32_e32 v10, v12, v12
	v_add_f32_e32 v1, v1, v10
	v_add_f32_e32 v1, v1, v7
	ds_bpermute_b32 v10, v188, v1
	v_cvt_pk_bf16_f32 v9, v8, v9
	v_cvt_pk_bf16_f32 v8, v0, v11
	v_lshlrev_b32_e32 v0, 3, v132
	v_cvt_pk_bf16_f32 v2, v2, v24
	v_cvt_pk_bf16_f32 v7, v12, v13
	s_and_saveexec_b64 s[28:29], s[8:9]
	s_cbranch_execz .LBB0_601
	s_lshl_b32 s0, s13, 2
	s_add_i32 s0, s0, 0
	s_waitcnt lgkmcnt(0)
	v_add_f32_e32 v1, v1, v10
	v_add_u32_e32 v10, s0, v0
	ds_write_b32 v10, v1 offset:34816

;     __device__ __forceinline__ const float* in(int i) const { return karg_in(i); }
; template <bool PASS2>
; __device__ __forceinline__ void s5_tile(const Ctx& C, int T, int sb_lo, int sb_hi, LAS unsigned char* lds, int wave, int lane) {
;     ...
;     const float* LAM = C.LAM();
;     const bf16* Zb = C.Z() + (size_t)1024 + 64 * wave;
;     float sr[4], si[4], lr[4], li[4], dsk[4];
; #pragma unroll
;     for (int gi = 0; gi < 4; ++gi) { const int g = wave * 4 + gi; sr[gi] = 0.f; si[gi] = 0.f; lr[gi] = LAM[0 * 2048 + g * 64 + lane]; li[gi] = LAM[1 * 2048 + g * 64 + lane];
;         dsk[gi] = PASS2 ? C.in(21)[16 * g + fr] : 0.f; }
;     if (PASS2 && !sample) {
;         const int k = T & 127, tb = T - k;
;         float l8r[4], l8i[4];
; #pragma unroll
;         for (int gi = 0; gi < 4; ++gi) { l8r[gi] = LAM[2 * 2048 + (wave * 4 + gi) * 64 + lane]; l8i[gi] = LAM[3 * 2048 + (wave * 4 + gi) * 64 + lane]; }
;         const v2f* Ep = (const v2f*)C.E() + ((size_t)tb * NG + wave * 4) * NP + lane;
;         const int nb = (k + 15) >> 4, j0 = k - 16 * nb;
.Lmy_p6_tile_entry:
	s_mov_b64 s[0:1], s[80:81]
	s_load_dwordx2 s[10:11], s[0:1], 0x110
	v_readfirstlane_b32 s3, v160
	s_ashr_i32 s67, s3, 6
	s_mov_b64 s[0:1], s[80:81]
	s_mov_b64 s[12:13], s[80:81]
	s_waitcnt lgkmcnt(0)
	s_add_u32 s10, s10, 0x2a40000
	s_addc_u32 s11, s11, 0
	s_lshl_b32 s14, s67, 8
	v_or_b32_e32 v0, s14, v98
	v_ashrrev_i32_e32 v1, 31, v0
	v_add_u32_e32 v2, s14, v103
	v_lshl_add_u64 v[0:1], v[0:1], 2, s[10:11]
	v_ashrrev_i32_e32 v3, 31, v2
	v_lshl_add_u64 v[2:3], v[2:3], 2, s[10:11]
	global_load_dword v173, v[0:1], off
	global_load_dword v174, v[2:3], off
	s_load_dwordx2 s[12:13], s[12:13], 0xa8
	s_and_b32 s72, s3, 0xffffffc0
	s_lshl_b32 s62, s67, 2
	v_or_b32_e32 v6, s72, v99
	v_ashrrev_i32_e32 v7, 31, v6
	s_or_b32 s64, s62, 1
	s_waitcnt lgkmcnt(0)
	v_lshl_add_u64 v[0:1], v[6:7], 2, s[12:13]
	s_lshl_b32 s3, s64, 6
	global_load_dword v175, v[0:1], off
	v_or_b32_e32 v0, s3, v98
	v_ashrrev_i32_e32 v1, 31, v0
	v_add_u32_e32 v2, s3, v103
	v_lshl_add_u64 v[0:1], v[0:1], 2, s[10:11]
	v_ashrrev_i32_e32 v3, 31, v2
	s_mov_b64 s[12:13], s[80:81]
	v_lshl_add_u64 v[2:3], v[2:3], 2, s[10:11]
	global_load_dword v176, v[0:1], off
	global_load_dword v177, v[2:3], off
	s_load_dwordx2 s[12:13], s[12:13], 0xa8
	v_lshl_or_b32 v4, s64, 4, v99
	v_ashrrev_i32_e32 v5, 31, v4
	s_or_b32 s66, s62, 2
	s_lshl_b32 s3, s66, 6
	s_waitcnt lgkmcnt(0)
	v_lshl_add_u64 v[0:1], v[4:5], 2, s[12:13]
	global_load_dword v178, v[0:1], off
	v_or_b32_e32 v0, s3, v98
	v_ashrrev_i32_e32 v1, 31, v0
	v_add_u32_e32 v2, s3, v103
	v_lshl_add_u64 v[0:1], v[0:1], 2, s[10:11]
	v_ashrrev_i32_e32 v3, 31, v2
	s_mov_b64 s[12:13], s[80:81]
	v_lshl_add_u64 v[2:3], v[2:3], 2, s[10:11]
	global_load_dword v179, v[0:1], off
	global_load_dword v180, v[2:3], off
	s_load_dwordx2 s[12:13], s[12:13], 0xa8
	v_lshl_or_b32 v2, s66, 4, v99
	v_ashrrev_i32_e32 v3, 31, v2
	s_or_b32 s68, s62, 3
	s_lshl_b32 s3, s68, 6
	s_waitcnt lgkmcnt(0)
	v_lshl_add_u64 v[0:1], v[2:3], 2, s[12:13]
	global_load_dword v181, v[0:1], off
	v_or_b32_e32 v0, s3, v98
	v_ashrrev_i32_e32 v1, 31, v0
	v_add_u32_e32 v8, s3, v103
	v_lshl_add_u64 v[0:1], v[0:1], 2, s[10:11]
	v_ashrrev_i32_e32 v9, 31, v8
	s_mov_b64 s[12:13], s[80:81]
	v_lshl_add_u64 v[8:9], v[8:9], 2, s[10:11]
	global_load_dword v189, v[0:1], off
	global_load_dword v190, v[8:9], off
	s_load_dwordx2 s[12:13], s[12:13], 0xa8
	v_lshl_or_b32 v0, s68, 4, v99
	v_ashrrev_i32_e32 v1, 31, v0
	s_or_b32 s3, s14, 64
	v_add_u32_e32 v12, s3, v105
	s_waitcnt lgkmcnt(0)
	v_lshl_add_u64 v[8:9], v[0:1], 2, s[12:13]
	v_add_u32_e32 v14, s3, v163
	s_or_b32 s3, s14, 0x80
	global_load_dword v191, v[8:9], off
	v_add_u32_e32 v8, s14, v105
	v_add_u32_e32 v10, s14, v163
	v_add_u32_e32 v16, s3, v105
	v_add_u32_e32 v18, s3, v163
	s_or_b32 s3, s14, 0xc0
	v_ashrrev_i32_e32 v9, 31, v8
	v_ashrrev_i32_e32 v11, 31, v10
	v_ashrrev_i32_e32 v13, 31, v12
	v_ashrrev_i32_e32 v15, 31, v14
	v_add_u32_e32 v20, s3, v105
	v_add_u32_e32 v22, s3, v163
	v_lshl_add_u64 v[8:9], v[8:9], 2, s[10:11]
	v_lshl_add_u64 v[10:11], v[10:11], 2, s[10:11]
	v_lshl_add_u64 v[12:13], v[12:13], 2, s[10:11]
	v_lshl_add_u64 v[14:15], v[14:15], 2, s[10:11]
	v_ashrrev_i32_e32 v17, 31, v16
	v_ashrrev_i32_e32 v19, 31, v18
	v_ashrrev_i32_e32 v21, 31, v20
	v_ashrrev_i32_e32 v23, 31, v22
	v_lshl_add_u64 v[16:17], v[16:17], 2, s[10:11]
	v_lshl_add_u64 v[18:19], v[18:19], 2, s[10:11]
	v_lshl_add_u64 v[20:21], v[20:21], 2, s[10:11]
	v_lshl_add_u64 v[22:23], v[22:23], 2, s[10:11]
	global_load_dword v8, v[8:9], off
	s_nop 0
	global_load_dword v10, v[10:11], off
	s_nop 0
	global_load_dword v9, v[12:13], off
	global_load_dword v11, v[14:15], off
	s_nop 0
	global_load_dword v12, v[16:17], off
	global_load_dword v14, v[18:19], off
	global_load_dword v13, v[20:21], off
	global_load_dword v15, v[22:23], off
	s_and_b32 s65, s77, 0x7f
	s_ashr_i32 s63, s62, 31
	s_mov_b64 s[10:11], s[80:81]
	s_cmp_eq_u32 s65, 0
	s_cbranch_scc1 .LBB0_664
; template <bool PASS2>
; __device__ __forceinline__ void s5_tile(const Ctx& C, int T, int sb_lo, int sb_hi, LAS unsigned char* lds, int wave, int lane) {
;     ...
;         const v2f* Ep = (const v2f*)C.E() + ((size_t)tb * NG + wave * 4) * NP + lane;
;         const int nb = (k + 15) >> 4, j0 = k - 16 * nb;
;         for (int jb = 0; jb < nb; ++jb) {
; #pragma unroll
;             for (int u = 0; u < 16; ++u) {
;                 const int j = j0 + 16 * jb + u; const bool ok = j >= 0; const int jc = ok ? j : 0;
; #pragma unroll
;                 for (int gi = 0; gi < 4; ++gi) { v2f e = Ep[(size_t)jc * NG * NP + gi * NP]; if (!ok) e = (v2f){0.f, 0.f};
;                     const float nr = fmaf(l8r[gi], sr[gi], fmaf(-l8i[gi], si[gi], e.x)), ni = fmaf(l8r[gi], si[gi], fmaf(l8i[gi], sr[gi], e.y)); sr[gi] = nr; si[gi] = ni; }
;             }
	s_load_dwordx2 s[10:11], s[10:11], 0x110
	s_and_b32 s12, s77, 0xffffff80
	s_ashr_i32 s13, s12, 31
	s_lshl_b64 s[12:13], s[12:13], 14
	v_lshlrev_b32_e32 v100, 3, v98
	s_waitcnt lgkmcnt(0)
	s_add_u32 s3, s10, s12
	s_addc_u32 s12, s11, s13
	s_lshl_b64 s[10:11], s[62:63], 9
	s_add_u32 s10, s3, s10
	s_addc_u32 s11, s12, s11
	s_and_b32 s3, s76, 0x7f
	v_lshl_add_u64 v[16:17], s[10:11], 0, v[100:101]
	v_mov_b32_e32 v114, 0
	v_lshl_add_u64 v[16:17], v[16:17], 0, s[56:57]
	v_mov_b32_e32 v115, v114
	v_mov_b32_e32 v110, v114
	v_mov_b32_e32 v111, v114
	v_mov_b32_e32 v112, v114
	v_mov_b32_e32 v113, v114
	v_mov_b32_e32 v108, v114
	v_mov_b32_e32 v109, v114
	s_add_i32 s10, s3, 7
	s_lshr_b32 s69, s10, 3
	s_lshl_b32 s10, s69, 3
	s_sub_i32 s73, s3, s10
	s_add_i32 s69, s69, -1
	s_mov_b32 s11, 0
	s_add_i32 s12, s73, 0
	s_max_i32 s12, s12, 0
	s_lshl_b32 s10, s12, 14
	v_lshl_add_u64 v[18:19], v[16:17], 0, s[10:11]
	global_load_dwordx2 v[20:21], v[18:19], off
	global_load_dwordx2 v[22:23], v[18:19], off offset:512
	global_load_dwordx2 v[24:25], v[18:19], off offset:1024
	global_load_dwordx2 v[26:27], v[18:19], off offset:1536
	s_add_i32 s12, s73, 1
	s_max_i32 s12, s12, 0
	s_lshl_b32 s10, s12, 14
	v_lshl_add_u64 v[18:19], v[16:17], 0, s[10:11]
	global_load_dwordx2 v[28:29], v[18:19], off
	global_load_dwordx2 v[30:31], v[18:19], off offset:512
	global_load_dwordx2 v[32:33], v[18:19], off offset:1024
	global_load_dwordx2 v[34:35], v[18:19], off offset:1536
	s_add_i32 s12, s73, 2
	s_max_i32 s12, s12, 0
	s_lshl_b32 s10, s12, 14
	v_lshl_add_u64 v[18:19], v[16:17], 0, s[10:11]
	global_load_dwordx2 v[36:37], v[18:19], off
	global_load_dwordx2 v[38:39], v[18:19], off offset:512
	global_load_dwordx2 v[40:41], v[18:19], off offset:1024
	global_load_dwordx2 v[42:43], v[18:19], off offset:1536
	s_add_i32 s12, s73, 3
	s_max_i32 s12, s12, 0
	s_lshl_b32 s10, s12, 14
	v_lshl_add_u64 v[18:19], v[16:17], 0, s[10:11]
	global_load_dwordx2 v[44:45], v[18:19], off
	global_load_dwordx2 v[46:47], v[18:19], off offset:512
	global_load_dwordx2 v[48:49], v[18:19], off offset:1024
	global_load_dwordx2 v[50:51], v[18:19], off offset:1536
	s_add_i32 s12, s73, 4
	s_max_i32 s12, s12, 0
	s_lshl_b32 s10, s12, 14
	v_lshl_add_u64 v[18:19], v[16:17], 0, s[10:11]
	global_load_dwordx2 v[52:53], v[18:19], off
	global_load_dwordx2 v[54:55], v[18:19], off offset:512
	global_load_dwordx2 v[56:57], v[18:19], off offset:1024
	global_load_dwordx2 v[58:59], v[18:19], off offset:1536
	s_add_i32 s12, s73, 5
	s_max_i32 s12, s12, 0
	s_lshl_b32 s10, s12, 14
	v_lshl_add_u64 v[18:19], v[16:17], 0, s[10:11]
	global_load_dwordx2 v[60:61], v[18:19], off
	global_load_dwordx2 v[62:63], v[18:19], off offset:512
	global_load_dwordx2 v[64:65], v[18:19], off offset:1024
	global_load_dwordx2 v[66:67], v[18:19], off offset:1536
	s_add_i32 s12, s73, 6
	s_max_i32 s12, s12, 0
	s_lshl_b32 s10, s12, 14
	v_lshl_add_u64 v[18:19], v[16:17], 0, s[10:11]
	global_load_dwordx2 v[68:69], v[18:19], off
	global_load_dwordx2 v[70:71], v[18:19], off offset:512
	global_load_dwordx2 v[72:73], v[18:19], off offset:1024
	global_load_dwordx2 v[74:75], v[18:19], off offset:1536
	s_add_i32 s12, s73, 7
	s_max_i32 s12, s12, 0
	s_lshl_b32 s10, s12, 14
	v_lshl_add_u64 v[18:19], v[16:17], 0, s[10:11]
	global_load_dwordx2 v[76:77], v[18:19], off
	global_load_dwordx2 v[78:79], v[18:19], off offset:512
	global_load_dwordx2 v[80:81], v[18:19], off offset:1024
	global_load_dwordx2 v[82:83], v[18:19], off offset:1536
	s_cmp_eq_u32 s69, 0
	s_cbranch_scc1 .Lmy_h_last

; template <bool PASS2>
; __device__ __forceinline__ void s5_tile(const Ctx& C, int T, int sb_lo, int sb_hi, LAS unsigned char* lds, int wave, int lane) {
;     ...
;         for (int jb = 0; jb < nb; ++jb) {
; #pragma unroll
;             for (int u = 0; u < 16; ++u) {
;                 const int j = j0 + 16 * jb + u; const bool ok = j >= 0; const int jc = ok ? j : 0;
; #pragma unroll
;                 for (int gi = 0; gi < 4; ++gi) { v2f e = Ep[(size_t)jc * NG * NP + gi * NP]; if (!ok) e = (v2f){0.f, 0.f};
;                     const float nr = fmaf(l8r[gi], sr[gi], fmaf(-l8i[gi], si[gi], e.x)), ni = fmaf(l8r[gi], si[gi], fmaf(l8i[gi], sr[gi], e.y)); sr[gi] = nr; si[gi] = ni; }
;             }
.Lmy_h_skipA0:
	s_add_i32 s12, s12, 8
	s_lshl_b32 s10, s12, 14
	v_lshl_add_u64 v[18:19], v[16:17], 0, s[10:11]
	global_load_dwordx2 v[20:21], v[18:19], off
	global_load_dwordx2 v[22:23], v[18:19], off offset:512
	global_load_dwordx2 v[24:25], v[18:19], off offset:1024
	global_load_dwordx2 v[26:27], v[18:19], off offset:1536
	s_waitcnt vmcnt(28)
	s_add_i32 s12, s73, 1
	s_cmp_lt_i32 s12, 0
	s_cbranch_scc1 .Lmy_h_skipA1
	v_fma_f32 v28, -v10, v112, v28
	v_fma_f32 v29, v10, v114, v29
	v_fma_f32 v30, -v11, v113, v30
	v_fma_f32 v31, v11, v115, v31
	v_fma_f32 v32, -v14, v108, v32
	v_fma_f32 v33, v14, v110, v33
	v_fma_f32 v34, -v15, v109, v34
	v_fma_f32 v35, v15, v111, v35
	v_fma_f32 v114, v8, v114, v28
	v_fma_f32 v112, v8, v112, v29
	v_fma_f32 v115, v9, v115, v30
	v_fma_f32 v113, v9, v113, v31
	v_fma_f32 v110, v12, v110, v32
	v_fma_f32 v108, v12, v108, v33
	v_fma_f32 v111, v13, v111, v34
	v_fma_f32 v109, v13, v109, v35
.Lmy_h_skipA1:
	s_add_i32 s12, s12, 8
	s_lshl_b32 s10, s12, 14
	v_lshl_add_u64 v[18:19], v[16:17], 0, s[10:11]
	global_load_dwordx2 v[28:29], v[18:19], off
	global_load_dwordx2 v[30:31], v[18:19], off offset:512
	global_load_dwordx2 v[32:33], v[18:19], off offset:1024
	global_load_dwordx2 v[34:35], v[18:19], off offset:1536
	s_waitcnt vmcnt(28)
	s_add_i32 s12, s73, 2
	s_cmp_lt_i32 s12, 0
	s_cbranch_scc1 .Lmy_h_skipA2
	v_fma_f32 v36, -v10, v112, v36
	v_fma_f32 v37, v10, v114, v37
	v_fma_f32 v38, -v11, v113, v38
	v_fma_f32 v39, v11, v115, v39
	v_fma_f32 v40, -v14, v108, v40
	v_fma_f32 v41, v14, v110, v41
	v_fma_f32 v42, -v15, v109, v42
	v_fma_f32 v43, v15, v111, v43
	v_fma_f32 v114, v8, v114, v36
	v_fma_f32 v112, v8, v112, v37
	v_fma_f32 v115, v9, v115, v38
	v_fma_f32 v113, v9, v113, v39
	v_fma_f32 v110, v12, v110, v40
	v_fma_f32 v108, v12, v108, v41
	v_fma_f32 v111, v13, v111, v42
	v_fma_f32 v109, v13, v109, v43
.Lmy_h_skipA2:
	s_add_i32 s12, s12, 8
	s_lshl_b32 s10, s12, 14
	v_lshl_add_u64 v[18:19], v[16:17], 0, s[10:11]
	global_load_dwordx2 v[36:37], v[18:19], off
	global_load_dwordx2 v[38:39], v[18:19], off offset:512
	global_load_dwordx2 v[40:41], v[18:19], off offset:1024
	global_load_dwordx2 v[42:43], v[18:19], off offset:1536
	s_waitcnt vmcnt(28)
	s_add_i32 s12, s73, 3
	s_cmp_lt_i32 s12, 0
	s_cbranch_scc1 .Lmy_h_skipA3
	v_fma_f32 v44, -v10, v112, v44
	v_fma_f32 v45, v10, v114, v45
	v_fma_f32 v46, -v11, v113, v46
	v_fma_f32 v47, v11, v115, v47
	v_fma_f32 v48, -v14, v108, v48
	v_fma_f32 v49, v14, v110, v49
	v_fma_f32 v50, -v15, v109, v50
	v_fma_f32 v51, v15, v111, v51
	v_fma_f32 v114, v8, v114, v44
	v_fma_f32 v112, v8, v112, v45
	v_fma_f32 v115, v9, v115, v46
	v_fma_f32 v113, v9, v113, v47
	v_fma_f32 v110, v12, v110, v48
	v_fma_f32 v108, v12, v108, v49
	v_fma_f32 v111, v13, v111, v50
	v_fma_f32 v109, v13, v109, v51
.Lmy_h_skipA3:
	s_add_i32 s12, s12, 8
	s_lshl_b32 s10, s12, 14
	v_lshl_add_u64 v[18:19], v[16:17], 0, s[10:11]
	global_load_dwordx2 v[44:45], v[18:19], off
	global_load_dwordx2 v[46:47], v[18:19], off offset:512
	global_load_dwordx2 v[48:49], v[18:19], off offset:1024
	global_load_dwordx2 v[50:51], v[18:19], off offset:1536
	s_waitcnt vmcnt(28)
	s_add_i32 s12, s73, 4
	s_cmp_lt_i32 s12, 0
	s_cbranch_scc1 .Lmy_h_skipA4
	v_fma_f32 v52, -v10, v112, v52
	v_fma_f32 v53, v10, v114, v53
	v_fma_f32 v54, -v11, v113, v54
	v_fma_f32 v55, v11, v115, v55
	v_fma_f32 v56, -v14, v108, v56
	v_fma_f32 v57, v14, v110, v57
	v_fma_f32 v58, -v15, v109, v58
	v_fma_f32 v59, v15, v111, v59
	v_fma_f32 v114, v8, v114, v52
	v_fma_f32 v112, v8, v112, v53
	v_fma_f32 v115, v9, v115, v54
	v_fma_f32 v113, v9, v113, v55
	v_fma_f32 v110, v12, v110, v56
	v_fma_f32 v108, v12, v108, v57
	v_fma_f32 v111, v13, v111, v58
	v_fma_f32 v109, v13, v109, v59
.Lmy_h_skipA4:
	s_add_i32 s12, s12, 8
	s_lshl_b32 s10, s12, 14
	v_lshl_add_u64 v[18:19], v[16:17], 0, s[10:11]
	global_load_dwordx2 v[52:53], v[18:19], off
	global_load_dwordx2 v[54:55], v[18:19], off offset:512
	global_load_dwordx2 v[56:57], v[18:19], off offset:1024
	global_load_dwordx2 v[58:59], v[18:19], off offset:1536
	s_waitcnt vmcnt(28)
	s_add_i32 s12, s73, 5
	s_cmp_lt_i32 s12, 0
	s_cbranch_scc1 .Lmy_h_skipA5
	v_fma_f32 v60, -v10, v112, v60
	v_fma_f32 v61, v10, v114, v61
	v_fma_f32 v62, -v11, v113, v62
	v_fma_f32 v63, v11, v115, v63
	v_fma_f32 v64, -v14, v108, v64
	v_fma_f32 v65, v14, v110, v65
	v_fma_f32 v66, -v15, v109, v66
	v_fma_f32 v67, v15, v111, v67
	v_fma_f32 v114, v8, v114, v60
	v_fma_f32 v112, v8, v112, v61
	v_fma_f32 v115, v9, v115, v62
	v_fma_f32 v113, v9, v113, v63
	v_fma_f32 v110, v12, v110, v64
	v_fma_f32 v108, v12, v108, v65
	v_fma_f32 v111, v13, v111, v66
	v_fma_f32 v109, v13, v109, v67
.Lmy_h_skipA5:
	s_add_i32 s12, s12, 8
	s_lshl_b32 s10, s12, 14
	v_lshl_add_u64 v[18:19], v[16:17], 0, s[10:11]
	global_load_dwordx2 v[60:61], v[18:19], off
	global_load_dwordx2 v[62:63], v[18:19], off offset:512
	global_load_dwordx2 v[64:65], v[18:19], off offset:1024
	global_load_dwordx2 v[66:67], v[18:19], off offset:1536
	s_waitcnt vmcnt(28)
	s_add_i32 s12, s73, 6
	s_cmp_lt_i32 s12, 0
	s_cbranch_scc1 .Lmy_h_skipA6
	v_fma_f32 v68, -v10, v112, v68
	v_fma_f32 v69, v10, v114, v69
	v_fma_f32 v70, -v11, v113, v70
	v_fma_f32 v71, v11, v115, v71
	v_fma_f32 v72, -v14, v108, v72
	v_fma_f32 v73, v14, v110, v73
	v_fma_f32 v74, -v15, v109, v74
	v_fma_f32 v75, v15, v111, v75
	v_fma_f32 v114, v8, v114, v68
	v_fma_f32 v112, v8, v112, v69
	v_fma_f32 v115, v9, v115, v70
	v_fma_f32 v113, v9, v113, v71
	v_fma_f32 v110, v12, v110, v72
	v_fma_f32 v108, v12, v108, v73
	v_fma_f32 v111, v13, v111, v74
	v_fma_f32 v109, v13, v109, v75
.Lmy_h_skipA6:
	s_add_i32 s12, s12, 8
	s_lshl_b32 s10, s12, 14
	v_lshl_add_u64 v[18:19], v[16:17], 0, s[10:11]
	global_load_dwordx2 v[68:69], v[18:19], off
	global_load_dwordx2 v[70:71], v[18:19], off offset:512
	global_load_dwordx2 v[72:73], v[18:19], off offset:1024
	global_load_dwordx2 v[74:75], v[18:19], off offset:1536
	s_waitcnt vmcnt(28)
	s_add_i32 s12, s73, 7
	s_cmp_lt_i32 s12, 0
	s_cbranch_scc1 .Lmy_h_skipA7
	v_fma_f32 v76, -v10, v112, v76
	v_fma_f32 v77, v10, v114, v77
	v_fma_f32 v78, -v11, v113, v78
	v_fma_f32 v79, v11, v115, v79
	v_fma_f32 v80, -v14, v108, v80
	v_fma_f32 v81, v14, v110, v81
	v_fma_f32 v82, -v15, v109, v82
	v_fma_f32 v83, v15, v111, v83
	v_fma_f32 v114, v8, v114, v76
	v_fma_f32 v112, v8, v112, v77
	v_fma_f32 v115, v9, v115, v78
	v_fma_f32 v113, v9, v113, v79
	v_fma_f32 v110, v12, v110, v80
	v_fma_f32 v108, v12, v108, v81
	v_fma_f32 v111, v13, v111, v82
	v_fma_f32 v109, v13, v109, v83
.Lmy_h_skipA7:
	s_add_i32 s12, s12, 8
	s_lshl_b32 s10, s12, 14
	v_lshl_add_u64 v[18:19], v[16:17], 0, s[10:11]
	global_load_dwordx2 v[76:77], v[18:19], off
	global_load_dwordx2 v[78:79], v[18:19], off offset:512
	global_load_dwordx2 v[80:81], v[18:19], off offset:1024
	global_load_dwordx2 v[82:83], v[18:19], off offset:1536
	s_add_i32 s73, s73, 8
	s_add_i32 s69, s69, -1
	s_cmp_lg_u32 s69, 0
	s_cbranch_scc1 .Lmy_h_loop
